# row-pass wave sums: DPP adds + permlane16/32 swaps replace 6-hop ds_bpermute chains (bit-identical)
# speedup vs baseline: 1.0080x; 1.0024x over previous
.LBB0_912:
	v_lshl_add_u64 v[24:25], s[70:71], 0, v[22:23]
	v_add_co_u32_e32 v4, vcc, 0xf501000, v24
	s_waitcnt lgkmcnt(0)
	s_nop 0
	v_addc_co_u32_e32 v5, vcc, 0, v25, vcc
	v_add_co_u32_e32 v6, vcc, 0x5201000, v24
	s_nop 1
	v_addc_co_u32_e32 v7, vcc, 0, v25, vcc
	global_load_dwordx2 v[40:41], v[4:5], off offset:1024
	global_load_dwordx2 v[28:29], v[4:5], off offset:1536
	global_load_dwordx2 v[30:31], v[4:5], off offset:2048
	global_load_dwordx2 v[32:33], v[4:5], off offset:2560
	global_load_dwordx2 v[54:55], v[6:7], off offset:1024
	global_load_dwordx2 v[42:43], v[6:7], off offset:1536
	global_load_dwordx2 v[34:35], v[6:7], off offset:2048
	global_load_dwordx2 v[26:27], v[6:7], off offset:2560
	global_load_dwordx4 v[12:15], v[68:69], off
	global_load_dwordx4 v[16:19], v[68:69], off offset:1024
	global_load_dwordx4 v[8:11], v[68:69], off offset:2048
	s_nop 0
	global_load_dwordx4 v[4:7], v[68:69], off offset:3072
	s_waitcnt vmcnt(10)
	v_and_b32_e32 v44, 0xffff0000, v28
	v_lshlrev_b32_e32 v45, 16, v29
	v_and_b32_e32 v57, 0xffff0000, v40
	v_and_b32_e32 v58, 0xffff0000, v41
	v_lshlrev_b32_e32 v61, 16, v41
	v_lshlrev_b32_e32 v46, 16, v28
	v_and_b32_e32 v47, 0xffff0000, v29
	v_pk_mul_f32 v[28:29], v[44:45], v[44:45]
	v_lshlrev_b32_e32 v56, 16, v40
	v_mov_b32_e32 v60, v58
	v_mul_f32_e32 v36, v61, v61
	v_pk_fma_f32 v[64:65], v[46:47], v[46:47], v[28:29]
	s_waitcnt vmcnt(8)
	v_and_b32_e32 v29, 0xffff0000, v32
	v_mul_f32_e32 v28, v57, v57
	v_pk_fma_f32 v[62:63], v[60:61], v[60:61], v[36:37] op_sel_hi:[1,1,0]
	v_and_b32_e32 v38, 0xffff0000, v31
	v_lshlrev_b32_e32 v39, 16, v31
	v_lshlrev_b32_e32 v31, 16, v32
	v_pk_fma_f32 v[66:67], v[56:57], v[56:57], v[28:29] op_sel_hi:[1,1,0]
	v_lshlrev_b32_e32 v36, 16, v30
	v_and_b32_e32 v37, 0xffff0000, v30
	v_mov_b32_e32 v30, v66
	v_mov_b32_e32 v80, v62
	v_mov_b32_e32 v81, v31
	v_mul_f32_e32 v40, v29, v29
	v_pk_add_f32 v[62:63], v[66:67], v[62:63]
	v_pk_mul_f32 v[66:67], v[30:31], v[80:81]
	v_pk_add_f32 v[64:65], v[64:65], v[64:65] op_sel:[0,1] op_sel_hi:[1,0]
	v_mov_b32_e32 v63, v67
	v_mov_b32_e32 v65, v40
	v_mul_f32_e32 v28, v37, v37
	v_lshlrev_b32_e32 v32, 16, v33
	v_and_b32_e32 v33, 0xffff0000, v33
	v_pk_add_f32 v[62:63], v[62:63], v[64:65]
	v_pk_fma_f32 v[64:65], v[36:37], v[36:37], v[28:29] op_sel_hi:[1,1,0]
	v_mul_f32_e32 v28, v39, v39
	v_mul_f32_e32 v53, v32, v32
	v_mul_f32_e32 v59, v33, v33
	v_pk_fma_f32 v[66:67], v[38:39], v[38:39], v[28:29] op_sel_hi:[1,1,0]
	v_mov_b32_e32 v65, v59
	v_mov_b32_e32 v67, v53
	v_pk_add_f32 v[64:65], v[64:65], v[66:67]
	v_and_b32_e32 v59, s0, v41
	v_pk_add_f32 v[62:63], v[62:63], v[64:65]
	v_pk_mov_b32 v[58:59], v[60:61], v[58:59] op_sel:[1,0]
	v_add_f32_e32 v28, v62, v63
	s_waitcnt vmcnt(7)
	v_lshlrev_b32_e32 v62, 16, v54
	v_and_b32_e32 v63, 0xffff0000, v54
	v_lshlrev_b32_e32 v54, 16, v55
	v_and_b32_e32 v55, 0xffff0000, v55
	s_waitcnt lgkmcnt(0)
	s_nop 1
	v_add_f32_dpp v28, v28, v28 quad_perm:[1,0,3,2] row_mask:0xf bank_mask:0xf
	s_waitcnt lgkmcnt(0)
	s_nop 1
	v_add_f32_dpp v28, v28, v28 quad_perm:[2,3,0,1] row_mask:0xf bank_mask:0xf
	s_waitcnt lgkmcnt(0)
	s_nop 1
	v_add_f32_dpp v28, v28, v28 row_half_mirror row_mask:0xf bank_mask:0xf
	s_waitcnt lgkmcnt(0)
	s_nop 1
	v_add_f32_dpp v28, v28, v28 row_mirror row_mask:0xf bank_mask:0xf
	s_waitcnt lgkmcnt(0)
	v_mov_b32_e32 v30, v28
	s_nop 1
	v_permlane16_swap_b32_e32 v30, v28
	s_nop 1
	v_add_f32_e32 v28, v30, v28
	s_waitcnt lgkmcnt(0)
	v_mov_b32_e32 v30, v28
	s_nop 1
	v_permlane32_swap_b32_e32 v30, v28
	s_nop 1
	v_add_f32_e32 v28, v30, v28
	v_fmamk_f32 v28, v28, 0x3a800000, v219
	v_mul_f32_e32 v30, 0x4b800000, v28
	v_cmp_gt_f32_e32 vcc, s35, v28
	s_nop 1
	v_cndmask_b32_e32 v28, v28, v30, vcc
	v_rsq_f32_e32 v28, v28
	s_nop 0
	v_mul_f32_e32 v30, 0x45800000, v28
	v_cndmask_b32_e32 v40, v28, v30, vcc
	v_pk_mul_f32 v[56:57], v[40:41], v[56:57] op_sel_hi:[0,1]
	v_pk_mul_f32 v[58:59], v[40:41], v[58:59] op_sel_hi:[0,1]
	s_waitcnt vmcnt(3)
	v_pk_fma_f32 v[14:15], v[14:15], v[58:59], v[54:55]
	v_pk_fma_f32 v[12:13], v[12:13], v[56:57], v[62:63]
	s_and_b64 vcc, exec, s[12:13]
	s_cbranch_vccz .LBB0_927
	v_lshl_add_u64 v[54:55], v[24:25], 0, s[48:49]
	v_cvt_pk_bf16_f32 v56, v12, v13
	v_cvt_pk_bf16_f32 v57, v14, v15
	global_store_dwordx2 v[54:55], v[56:57], off
	s_cbranch_execnz .LBB0_915

.LBB0_924:
	s_and_b64 vcc, exec, s[12:13]
	s_cbranch_vccz .LBB0_911
	v_mul_f32_e32 v13, v13, v13
	v_fmac_f32_e32 v13, v12, v12
	v_mul_f32_e32 v12, v14, v14
	v_fmac_f32_e32 v12, v15, v15
	v_add_f32_e32 v12, v13, v12
	v_mul_f32_e32 v13, v17, v17
	v_mul_f32_e32 v14, v18, v18
	v_mul_f32_e32 v9, v9, v9
	v_fmac_f32_e32 v13, v16, v16
	v_fmac_f32_e32 v14, v19, v19
	v_fmac_f32_e32 v9, v8, v8
	v_mul_f32_e32 v8, v10, v10
	v_mul_f32_e32 v5, v5, v5
	v_add_f32_e32 v13, v13, v14
	v_fmac_f32_e32 v8, v11, v11
	v_fmac_f32_e32 v5, v4, v4
	v_mul_f32_e32 v4, v6, v6
	v_add_f32_e32 v12, v12, v13
	v_add_f32_e32 v8, v9, v8
	v_fmac_f32_e32 v4, v7, v7
	v_add_f32_e32 v8, v8, v12
	v_add_f32_e32 v4, v5, v4
	v_add_f32_e32 v4, v4, v8
	s_waitcnt lgkmcnt(0)
	s_nop 1
	v_add_f32_dpp v4, v4, v4 quad_perm:[1,0,3,2] row_mask:0xf bank_mask:0xf
	s_waitcnt lgkmcnt(0)
	s_nop 1
	v_add_f32_dpp v4, v4, v4 quad_perm:[2,3,0,1] row_mask:0xf bank_mask:0xf
	s_waitcnt lgkmcnt(0)
	s_nop 1
	v_add_f32_dpp v4, v4, v4 row_half_mirror row_mask:0xf bank_mask:0xf
	s_waitcnt lgkmcnt(0)
	s_nop 1
	v_add_f32_dpp v4, v4, v4 row_mirror row_mask:0xf bank_mask:0xf
	s_waitcnt lgkmcnt(0)
	v_mov_b32_e32 v5, v4
	s_nop 1
	v_permlane16_swap_b32_e32 v5, v4
	s_nop 1
	v_add_f32_e32 v4, v5, v4
	v_mov_b32_e32 v5, v4
	s_nop 1
	v_permlane32_swap_b32_e32 v5, v4
	s_nop 1
	s_and_saveexec_b64 s[16:17], s[42:43]
	s_cbranch_execz .LBB0_910
	s_waitcnt lgkmcnt(0)
	v_add_f32_e32 v4, v4, v5
	v_fmamk_f32 v4, v4, 0x3a800000, v219
	v_mul_f32_e32 v5, 0x4b800000, v4
	v_cmp_gt_f32_e32 vcc, s35, v4
	s_add_u32 s22, s70, s2
	s_addc_u32 s23, s71, s3
	v_cndmask_b32_e32 v4, v4, v5, vcc
	v_rsq_f32_e32 v4, v4
	s_nop 0
	v_mul_f32_e32 v5, 0x45800000, v4
	v_cndmask_b32_e32 v4, v4, v5, vcc
	global_store_dword v3, v4, s[22:23]
	s_branch .LBB0_910

.LBB0_932:
	s_and_b64 vcc, exec, s[2:3]
	s_cbranch_vccz .LBB0_907
	s_ashr_i32 s11, s10, 31
	s_sub_i32 s22, s20, s86
	s_lshl_b64 s[2:3], s[10:11], 11
	s_ashr_i32 s23, s22, 31
	s_waitcnt lgkmcnt(0)
	v_lshl_add_u64 v[4:5], v[72:73], 0, s[2:3]
	v_lshl_add_u64 v[102:103], v[74:75], 0, s[2:3]
	s_lshl_b64 s[2:3], s[22:23], 11
	global_load_dwordx2 v[16:17], v[4:5], off
	global_load_dwordx2 v[18:19], v[4:5], off offset:512
	global_load_dwordx2 v[34:35], v[4:5], off offset:1024
	global_load_dwordx2 v[104:105], v[4:5], off offset:1536
	global_load_dwordx2 v[108:109], v[102:103], off
	global_load_dwordx2 v[24:25], v[102:103], off offset:512
	global_load_dwordx2 v[28:29], v[102:103], off offset:1024
	global_load_dwordx2 v[32:33], v[102:103], off offset:1536
	v_lshl_add_u64 v[4:5], v[72:73], 0, s[2:3]
	v_lshl_add_u64 v[100:101], v[74:75], 0, s[2:3]
	s_add_i32 s2, s22, s90
	s_ashr_i32 s3, s2, 31
	s_lshl_b64 s[16:17], s[2:3], 11
	s_ashr_i32 s21, s20, 31
	global_load_dwordx2 v[50:51], v[4:5], off
	global_load_dwordx2 v[46:47], v[4:5], off offset:512
	global_load_dwordx2 v[42:43], v[4:5], off offset:1024
	global_load_dwordx2 v[38:39], v[4:5], off offset:1536
	global_load_dwordx2 v[36:37], v[100:101], off
	global_load_dwordx2 v[40:41], v[100:101], off offset:512
	global_load_dwordx2 v[44:45], v[100:101], off offset:1024
	global_load_dwordx2 v[48:49], v[100:101], off offset:1536
	v_lshl_add_u64 v[4:5], v[72:73], 0, s[16:17]
	v_lshl_add_u64 v[98:99], v[74:75], 0, s[16:17]
	s_lshl_b64 s[16:17], s[20:21], 11
	global_load_dwordx2 v[66:67], v[4:5], off
	global_load_dwordx2 v[62:63], v[4:5], off offset:512
	global_load_dwordx2 v[58:59], v[4:5], off offset:1024
	global_load_dwordx2 v[54:55], v[4:5], off offset:1536
	global_load_dwordx2 v[52:53], v[98:99], off
	global_load_dwordx2 v[56:57], v[98:99], off offset:512
	global_load_dwordx2 v[60:61], v[98:99], off offset:1024
	global_load_dwordx2 v[64:65], v[98:99], off offset:1536
	v_lshl_add_u64 v[4:5], v[72:73], 0, s[16:17]
	v_lshl_add_u64 v[80:81], v[74:75], 0, s[16:17]
	global_load_dwordx2 v[96:97], v[4:5], off
	global_load_dwordx2 v[94:95], v[4:5], off offset:512
	global_load_dwordx2 v[92:93], v[4:5], off offset:1024
	global_load_dwordx2 v[90:91], v[4:5], off offset:1536
	global_load_dwordx2 v[88:89], v[80:81], off
	global_load_dwordx2 v[86:87], v[80:81], off offset:512
	global_load_dwordx2 v[84:85], v[80:81], off offset:1024
	global_load_dwordx2 v[82:83], v[80:81], off offset:1536
	global_load_dwordx4 v[20:23], v[68:69], off
	global_load_dwordx4 v[12:15], v[68:69], off offset:1024
	global_load_dwordx4 v[8:11], v[68:69], off offset:2048
	global_load_dwordx4 v[4:7], v[68:69], off offset:3072
	v_and_b32_e32 v26, 64, v217
	s_waitcnt vmcnt(35)
	v_lshlrev_b32_e32 v110, 16, v16
	v_and_b32_e32 v111, 0xffff0000, v16
	v_lshlrev_b32_e32 v16, 16, v17
	v_and_b32_e32 v17, 0xffff0000, v17
	v_add_u32_e32 v124, 64, v26
	v_mul_f32_e32 v26, v17, v17
	s_waitcnt vmcnt(34)
	v_and_b32_e32 v113, 0xffff0000, v19
	v_and_b32_e32 v112, 0xffff0000, v18
	v_mul_f32_e32 v118, v111, v111
	v_pk_fma_f32 v[114:115], v[16:17], v[16:17], v[26:27] op_sel_hi:[1,1,0]
	v_lshlrev_b32_e32 v27, 16, v19
	v_lshlrev_b32_e32 v26, 16, v18
	v_pk_mul_f32 v[18:19], v[112:113], v[112:113]
	s_waitcnt vmcnt(33)
	v_lshlrev_b32_e32 v30, 16, v34
	v_and_b32_e32 v31, 0xffff0000, v34
	s_waitcnt vmcnt(32)
	v_lshlrev_b32_e32 v34, 16, v104
	v_pk_fma_f32 v[118:119], v[110:111], v[110:111], v[118:119] op_sel_hi:[1,1,0]
	v_pk_fma_f32 v[18:19], v[26:27], v[26:27], v[18:19]
	v_lshlrev_b32_e32 v106, 16, v35
	v_and_b32_e32 v107, 0xffff0000, v35
	v_and_b32_e32 v35, 0xffff0000, v104
	v_mov_b32_e32 v120, v118
	v_mov_b32_e32 v121, v34
	v_mov_b32_e32 v122, v114
	v_mov_b32_e32 v123, v34
	v_mul_f32_e32 v117, v35, v35
	v_pk_add_f32 v[114:115], v[118:119], v[114:115]
	v_pk_mul_f32 v[118:119], v[120:121], v[122:123]
	v_pk_add_f32 v[18:19], v[18:19], v[18:19] op_sel:[0,1] op_sel_hi:[1,0]
	v_mov_b32_e32 v115, v119
	v_mov_b32_e32 v19, v117
	v_lshlrev_b32_e32 v104, 16, v105
	v_and_b32_e32 v105, 0xffff0000, v105
	v_pk_add_f32 v[18:19], v[114:115], v[18:19]
	v_mul_f32_e32 v114, v31, v31
	v_mul_f32_e32 v118, v107, v107
	v_mul_f32_e32 v125, v104, v104
	v_mul_f32_e32 v126, v105, v105
	v_pk_fma_f32 v[114:115], v[30:31], v[30:31], v[114:115] op_sel_hi:[1,1,0]
	v_pk_fma_f32 v[118:119], v[106:107], v[106:107], v[118:119] op_sel_hi:[1,1,0]
	v_xor_b32_e32 v1, 1, v217
	v_mov_b32_e32 v115, v125
	v_mov_b32_e32 v119, v126
	v_cmp_lt_i32_e32 vcc, v1, v124
	v_pk_add_f32 v[114:115], v[114:115], v[118:119]
	s_nop 0
	v_cndmask_b32_e32 v1, v217, v1, vcc
	v_pk_add_f32 v[18:19], v[18:19], v[114:115]
	v_lshlrev_b32_e32 v1, 2, v1
	v_add_f32_e32 v18, v18, v19
	v_xor_b32_e32 v114, 2, v217
	v_cmp_lt_i32_e32 vcc, v114, v124
	s_waitcnt vmcnt(31)
	v_and_b32_e32 v115, 0xffff0000, v108
	s_waitcnt lgkmcnt(0)
	s_nop 1
	v_add_f32_dpp v18, v18, v18 quad_perm:[1,0,3,2] row_mask:0xf bank_mask:0xf
	v_cndmask_b32_e32 v114, v217, v114, vcc
	v_lshlrev_b32_e32 v117, 2, v114
	v_xor_b32_e32 v114, 4, v217
	v_cmp_lt_i32_e32 vcc, v114, v124
	s_waitcnt lgkmcnt(0)
	s_nop 1
	v_add_f32_dpp v18, v18, v18 quad_perm:[2,3,0,1] row_mask:0xf bank_mask:0xf
	v_cndmask_b32_e32 v114, v217, v114, vcc
	v_lshlrev_b32_e32 v118, 2, v114
	v_xor_b32_e32 v114, 8, v217
	v_cmp_lt_i32_e32 vcc, v114, v124
	s_waitcnt lgkmcnt(0)
	s_nop 1
	v_add_f32_dpp v18, v18, v18 row_half_mirror row_mask:0xf bank_mask:0xf
	v_cndmask_b32_e32 v114, v217, v114, vcc
	v_lshlrev_b32_e32 v119, 2, v114
	v_xor_b32_e32 v114, 16, v217
	v_cmp_lt_i32_e32 vcc, v114, v124
	s_waitcnt lgkmcnt(0)
	s_nop 1
	v_add_f32_dpp v18, v18, v18 row_mirror row_mask:0xf bank_mask:0xf
	v_cndmask_b32_e32 v114, v217, v114, vcc
	v_lshlrev_b32_e32 v120, 2, v114
	v_xor_b32_e32 v114, 32, v217
	v_cmp_lt_i32_e32 vcc, v114, v124
	s_waitcnt lgkmcnt(0)
	v_mov_b32_e32 v19, v18
	s_nop 1
	v_permlane16_swap_b32_e32 v19, v18
	s_nop 1
	v_add_f32_e32 v18, v19, v18
	v_cndmask_b32_e32 v114, v217, v114, vcc
	v_lshlrev_b32_e32 v121, 2, v114
	v_lshlrev_b32_e32 v114, 16, v108
	s_waitcnt lgkmcnt(0)
	v_mov_b32_e32 v19, v18
	s_nop 1
	v_permlane32_swap_b32_e32 v19, v18
	s_nop 1
	v_add_f32_e32 v18, v19, v18
	v_fmamk_f32 v18, v18, 0x3a800000, v219
	v_mul_f32_e32 v19, 0x4b800000, v18
	v_cmp_gt_f32_e32 vcc, s35, v18
	s_nop 1
	v_cndmask_b32_e32 v18, v18, v19, vcc
	v_rsq_f32_e32 v122, v18
	v_lshlrev_b32_e32 v18, 16, v109
	v_and_b32_e32 v19, 0xffff0000, v109
	v_mul_f32_e32 v108, 0x45800000, v122
	v_cndmask_b32_e32 v108, v122, v108, vcc
	v_pk_mul_f32 v[110:111], v[108:109], v[110:111] op_sel_hi:[0,1]
	v_pk_mul_f32 v[16:17], v[108:109], v[16:17] op_sel_hi:[0,1]
	s_waitcnt vmcnt(3)
	v_pk_fma_f32 v[18:19], v[22:23], v[16:17], v[18:19]
	v_pk_fma_f32 v[16:17], v[20:21], v[110:111], v[114:115]
	s_and_b64 vcc, exec, s[12:13]
	s_cbranch_vccz .LBB0_990
	v_cvt_pk_bf16_f32 v110, v16, v17
	v_cvt_pk_bf16_f32 v111, v18, v19
	global_store_dwordx2 v[102:103], v[110:111], off
	s_lshl_b64 s[26:27], s[10:11], 12
	v_lshl_add_u64 v[110:111], v[70:71], 0, s[26:27]
	s_cbranch_execnz .LBB0_936

.LBB0_945:
	v_and_b32_e32 v123, 0xffff0000, v51
	v_lshlrev_b32_e32 v110, 16, v50
	v_and_b32_e32 v111, 0xffff0000, v50
	v_lshlrev_b32_e32 v122, 16, v51
	v_mul_f32_e32 v50, v123, v123
	v_pk_fma_f32 v[108:109], v[122:123], v[122:123], v[50:51] op_sel_hi:[1,1,0]
	v_and_b32_e32 v115, 0xffff0000, v47
	v_and_b32_e32 v114, 0xffff0000, v46
	v_lshlrev_b32_e32 v103, 16, v38
	v_and_b32_e32 v51, 0xffff0000, v38
	v_mul_f32_e32 v38, v111, v111
	v_lshlrev_b32_e32 v113, 16, v47
	v_lshlrev_b32_e32 v112, 16, v46
	v_pk_mul_f32 v[46:47], v[114:115], v[114:115]
	v_lshlrev_b32_e32 v104, 16, v39
	v_and_b32_e32 v105, 0xffff0000, v39
	v_pk_fma_f32 v[38:39], v[110:111], v[110:111], v[38:39] op_sel_hi:[1,1,0]
	v_pk_fma_f32 v[124:125], v[112:113], v[112:113], v[46:47]
	v_lshlrev_b32_e32 v46, 16, v42
	v_and_b32_e32 v47, 0xffff0000, v42
	v_lshlrev_b32_e32 v106, 16, v43
	v_and_b32_e32 v107, 0xffff0000, v43
	v_mov_b32_e32 v102, v38
	v_mov_b32_e32 v42, v108
	v_mov_b32_e32 v43, v103
	v_pk_add_f32 v[38:39], v[38:39], v[108:109]
	v_pk_mul_f32 v[42:43], v[102:103], v[42:43]
	v_mul_f32_e32 v50, v51, v51
	v_mov_b32_e32 v39, v43
	v_pk_add_f32 v[42:43], v[124:125], v[124:125] op_sel:[0,1] op_sel_hi:[1,0]
	v_mul_f32_e32 v126, v104, v104
	v_mov_b32_e32 v43, v50
	v_pk_add_f32 v[38:39], v[38:39], v[42:43]
	v_mul_f32_e32 v42, v47, v47
	v_mul_f32_e32 v50, v107, v107
	v_mul_f32_e32 v127, v105, v105
	v_pk_fma_f32 v[42:43], v[46:47], v[46:47], v[42:43] op_sel_hi:[1,1,0]
	v_pk_fma_f32 v[108:109], v[106:107], v[106:107], v[50:51] op_sel_hi:[1,1,0]
	v_mov_b32_e32 v43, v126
	v_mov_b32_e32 v109, v127
	v_pk_add_f32 v[42:43], v[42:43], v[108:109]
	s_nop 0
	v_pk_add_f32 v[38:39], v[38:39], v[42:43]
	v_lshlrev_b32_e32 v42, 16, v36
	v_add_f32_e32 v38, v38, v39
	v_and_b32_e32 v43, 0xffff0000, v36
	v_lshlrev_b32_e32 v36, 16, v37
	v_and_b32_e32 v37, 0xffff0000, v37
	s_waitcnt lgkmcnt(0)
	s_nop 1
	v_add_f32_dpp v38, v38, v38 quad_perm:[1,0,3,2] row_mask:0xf bank_mask:0xf
	s_waitcnt lgkmcnt(0)
	s_nop 1
	v_add_f32_dpp v38, v38, v38 quad_perm:[2,3,0,1] row_mask:0xf bank_mask:0xf
	s_waitcnt lgkmcnt(0)
	s_nop 1
	v_add_f32_dpp v38, v38, v38 row_half_mirror row_mask:0xf bank_mask:0xf
	s_waitcnt lgkmcnt(0)
	s_nop 1
	v_add_f32_dpp v38, v38, v38 row_mirror row_mask:0xf bank_mask:0xf
	s_waitcnt lgkmcnt(0)
	v_mov_b32_e32 v39, v38
	s_nop 1
	v_permlane16_swap_b32_e32 v39, v38
	s_nop 1
	v_add_f32_e32 v38, v39, v38
	s_waitcnt lgkmcnt(0)
	v_mov_b32_e32 v39, v38
	s_nop 1
	v_permlane32_swap_b32_e32 v39, v38
	s_nop 1
	v_add_f32_e32 v38, v39, v38
	v_fmamk_f32 v38, v38, 0x3a800000, v219
	v_mul_f32_e32 v39, 0x4b800000, v38
	v_cmp_gt_f32_e32 vcc, s35, v38
	s_nop 1
	v_cndmask_b32_e32 v38, v38, v39, vcc
	v_rsq_f32_e32 v38, v38
	s_nop 0
	v_mul_f32_e32 v39, 0x45800000, v38
	v_cndmask_b32_e32 v108, v38, v39, vcc
	v_pk_mul_f32 v[110:111], v[108:109], v[110:111] op_sel_hi:[0,1]
	v_pk_mul_f32 v[38:39], v[108:109], v[122:123] op_sel_hi:[0,1]
	v_pk_fma_f32 v[38:39], v[22:23], v[38:39], v[36:37]
	s_and_b64 vcc, exec, s[46:47]
	v_pk_fma_f32 v[36:37], v[20:21], v[110:111], v[42:43]
	s_cbranch_vccnz .LBB0_994
	v_cvt_pk_bf16_f32 v42, v36, v37
	v_cvt_pk_bf16_f32 v43, v38, v39
	global_store_dwordx2 v[100:101], v[42:43], off
	s_lshl_b64 s[26:27], s[22:23], 12
	v_lshl_add_u64 v[110:111], v[70:71], 0, s[26:27]
	s_cbranch_execnz .LBB0_948

.LBB0_957:
	v_and_b32_e32 v115, 0xffff0000, v67
	v_lshlrev_b32_e32 v108, 16, v66
	v_and_b32_e32 v109, 0xffff0000, v66
	v_lshlrev_b32_e32 v114, 16, v67
	v_mul_f32_e32 v66, v115, v115
	v_pk_fma_f32 v[106:107], v[114:115], v[114:115], v[66:67] op_sel_hi:[1,1,0]
	v_and_b32_e32 v113, 0xffff0000, v63
	v_and_b32_e32 v112, 0xffff0000, v62
	v_lshlrev_b32_e32 v101, 16, v54
	v_and_b32_e32 v67, 0xffff0000, v54
	v_mul_f32_e32 v54, v109, v109
	v_lshlrev_b32_e32 v111, 16, v63
	v_lshlrev_b32_e32 v110, 16, v62
	v_pk_mul_f32 v[62:63], v[112:113], v[112:113]
	v_lshlrev_b32_e32 v102, 16, v55
	v_and_b32_e32 v103, 0xffff0000, v55
	v_pk_fma_f32 v[54:55], v[108:109], v[108:109], v[54:55] op_sel_hi:[1,1,0]
	v_pk_fma_f32 v[122:123], v[110:111], v[110:111], v[62:63]
	v_lshlrev_b32_e32 v62, 16, v58
	v_and_b32_e32 v63, 0xffff0000, v58
	v_lshlrev_b32_e32 v104, 16, v59
	v_and_b32_e32 v105, 0xffff0000, v59
	v_mov_b32_e32 v100, v54
	v_mov_b32_e32 v58, v106
	v_mov_b32_e32 v59, v101
	v_pk_add_f32 v[54:55], v[54:55], v[106:107]
	v_pk_mul_f32 v[58:59], v[100:101], v[58:59]
	v_mul_f32_e32 v66, v67, v67
	v_mov_b32_e32 v55, v59
	v_pk_add_f32 v[58:59], v[122:123], v[122:123] op_sel:[0,1] op_sel_hi:[1,0]
	v_mul_f32_e32 v124, v102, v102
	v_mov_b32_e32 v59, v66
	v_pk_add_f32 v[54:55], v[54:55], v[58:59]
	v_mul_f32_e32 v58, v63, v63
	v_mul_f32_e32 v66, v105, v105
	v_mul_f32_e32 v125, v103, v103
	v_pk_fma_f32 v[58:59], v[62:63], v[62:63], v[58:59] op_sel_hi:[1,1,0]
	v_pk_fma_f32 v[106:107], v[104:105], v[104:105], v[66:67] op_sel_hi:[1,1,0]
	v_mov_b32_e32 v59, v124
	v_mov_b32_e32 v107, v125
	v_pk_add_f32 v[58:59], v[58:59], v[106:107]
	s_nop 0
	v_pk_add_f32 v[54:55], v[54:55], v[58:59]
	v_lshlrev_b32_e32 v58, 16, v52
	v_add_f32_e32 v54, v54, v55
	v_and_b32_e32 v59, 0xffff0000, v52
	v_lshlrev_b32_e32 v52, 16, v53
	v_and_b32_e32 v53, 0xffff0000, v53
	s_waitcnt lgkmcnt(0)
	s_nop 1
	v_add_f32_dpp v54, v54, v54 quad_perm:[1,0,3,2] row_mask:0xf bank_mask:0xf
	s_waitcnt lgkmcnt(0)
	s_nop 1
	v_add_f32_dpp v54, v54, v54 quad_perm:[2,3,0,1] row_mask:0xf bank_mask:0xf
	s_waitcnt lgkmcnt(0)
	s_nop 1
	v_add_f32_dpp v54, v54, v54 row_half_mirror row_mask:0xf bank_mask:0xf
	s_waitcnt lgkmcnt(0)
	s_nop 1
	v_add_f32_dpp v54, v54, v54 row_mirror row_mask:0xf bank_mask:0xf
	s_waitcnt lgkmcnt(0)
	v_mov_b32_e32 v55, v54
	s_nop 1
	v_permlane16_swap_b32_e32 v55, v54
	s_nop 1
	v_add_f32_e32 v54, v55, v54
	s_waitcnt lgkmcnt(0)
	v_mov_b32_e32 v55, v54
	s_nop 1
	v_permlane32_swap_b32_e32 v55, v54
	s_nop 1
	v_add_f32_e32 v54, v55, v54
	v_fmamk_f32 v54, v54, 0x3a800000, v219
	v_mul_f32_e32 v55, 0x4b800000, v54
	v_cmp_gt_f32_e32 vcc, s35, v54
	s_nop 1
	v_cndmask_b32_e32 v54, v54, v55, vcc
	v_rsq_f32_e32 v54, v54
	s_nop 0
	v_mul_f32_e32 v55, 0x45800000, v54
	v_cndmask_b32_e32 v106, v54, v55, vcc
	v_pk_mul_f32 v[108:109], v[106:107], v[108:109] op_sel_hi:[0,1]
	v_pk_mul_f32 v[54:55], v[106:107], v[114:115] op_sel_hi:[0,1]
	v_pk_fma_f32 v[54:55], v[22:23], v[54:55], v[52:53]
	s_and_b64 vcc, exec, s[46:47]
	v_pk_fma_f32 v[52:53], v[20:21], v[108:109], v[58:59]
	s_cbranch_vccnz .LBB0_998
	v_cvt_pk_bf16_f32 v58, v52, v53
	v_cvt_pk_bf16_f32 v59, v54, v55
	global_store_dwordx2 v[98:99], v[58:59], off
	s_lshl_b64 s[26:27], s[2:3], 12
	v_lshl_add_u64 v[108:109], v[70:71], 0, s[26:27]
	s_cbranch_execnz .LBB0_960

.LBB0_969:
	v_and_b32_e32 v107, 0xffff0000, v97
	v_lshlrev_b32_e32 v100, 16, v96
	v_and_b32_e32 v101, 0xffff0000, v96
	v_lshlrev_b32_e32 v106, 16, v97
	v_mul_f32_e32 v96, v107, v107
	v_and_b32_e32 v105, 0xffff0000, v95
	v_and_b32_e32 v104, 0xffff0000, v94
	v_pk_fma_f32 v[108:109], v[106:107], v[106:107], v[96:97] op_sel_hi:[1,1,0]
	v_lshlrev_b32_e32 v103, 16, v95
	v_lshlrev_b32_e32 v102, 16, v94
	v_pk_mul_f32 v[94:95], v[104:105], v[104:105]
	v_lshlrev_b32_e32 v96, 16, v92
	v_and_b32_e32 v97, 0xffff0000, v92
	v_lshlrev_b32_e32 v98, 16, v93
	v_and_b32_e32 v99, 0xffff0000, v93
	v_and_b32_e32 v93, 0xffff0000, v90
	v_mul_f32_e32 v92, v101, v101
	v_pk_fma_f32 v[110:111], v[102:103], v[102:103], v[94:95]
	v_lshlrev_b32_e32 v95, 16, v90
	v_pk_fma_f32 v[112:113], v[100:101], v[100:101], v[92:93] op_sel_hi:[1,1,0]
	v_mov_b32_e32 v114, v108
	v_mov_b32_e32 v94, v112
	v_mov_b32_e32 v115, v95
	v_mul_f32_e32 v122, v93, v93
	v_pk_add_f32 v[108:109], v[112:113], v[108:109]
	v_pk_mul_f32 v[112:113], v[94:95], v[114:115]
	v_pk_add_f32 v[110:111], v[110:111], v[110:111] op_sel:[0,1] op_sel_hi:[1,0]
	v_mov_b32_e32 v109, v113
	v_mov_b32_e32 v111, v122
	v_mul_f32_e32 v92, v97, v97
	v_lshlrev_b32_e32 v90, 16, v91
	v_and_b32_e32 v91, 0xffff0000, v91
	v_pk_add_f32 v[108:109], v[108:109], v[110:111]
	v_pk_fma_f32 v[110:111], v[96:97], v[96:97], v[92:93] op_sel_hi:[1,1,0]
	v_mul_f32_e32 v92, v99, v99
	v_mul_f32_e32 v123, v90, v90
	v_mul_f32_e32 v124, v91, v91
	v_pk_fma_f32 v[112:113], v[98:99], v[98:99], v[92:93] op_sel_hi:[1,1,0]
	v_mov_b32_e32 v111, v123
	v_mov_b32_e32 v113, v124
	v_pk_add_f32 v[110:111], v[110:111], v[112:113]
	s_nop 0
	v_pk_add_f32 v[108:109], v[108:109], v[110:111]
	v_lshlrev_b32_e32 v110, 16, v89
	v_add_f32_e32 v92, v108, v109
	v_lshlrev_b32_e32 v108, 16, v88
	v_and_b32_e32 v109, 0xffff0000, v88
	v_and_b32_e32 v111, 0xffff0000, v89
	s_waitcnt lgkmcnt(0)
	s_nop 1
	v_add_f32_dpp v92, v92, v92 quad_perm:[1,0,3,2] row_mask:0xf bank_mask:0xf
	s_waitcnt lgkmcnt(0)
	s_nop 1
	v_add_f32_dpp v92, v92, v92 quad_perm:[2,3,0,1] row_mask:0xf bank_mask:0xf
	s_waitcnt lgkmcnt(0)
	s_nop 1
	v_add_f32_dpp v92, v92, v92 row_half_mirror row_mask:0xf bank_mask:0xf
	s_waitcnt lgkmcnt(0)
	s_nop 1
	v_add_f32_dpp v92, v92, v92 row_mirror row_mask:0xf bank_mask:0xf
	s_waitcnt lgkmcnt(0)
	v_mov_b32_e32 v94, v92
	s_nop 1
	v_permlane16_swap_b32_e32 v94, v92
	s_nop 1
	v_add_f32_e32 v92, v94, v92
	s_waitcnt lgkmcnt(0)
	v_mov_b32_e32 v94, v92
	s_nop 1
	v_permlane32_swap_b32_e32 v94, v92
	s_nop 1
	v_add_f32_e32 v92, v94, v92
	v_fmamk_f32 v92, v92, 0x3a800000, v219
	v_mul_f32_e32 v94, 0x4b800000, v92
	v_cmp_gt_f32_e32 vcc, s35, v92
	s_nop 1
	v_cndmask_b32_e32 v92, v92, v94, vcc
	v_rsq_f32_e32 v92, v92
	s_nop 0
	v_mul_f32_e32 v88, 0x45800000, v92
	v_cndmask_b32_e32 v88, v92, v88, vcc
	v_pk_mul_f32 v[100:101], v[88:89], v[100:101] op_sel_hi:[0,1]
	v_pk_mul_f32 v[106:107], v[88:89], v[106:107] op_sel_hi:[0,1]
	v_pk_fma_f32 v[22:23], v[22:23], v[106:107], v[110:111]
	s_and_b64 vcc, exec, s[46:47]
	v_pk_fma_f32 v[20:21], v[20:21], v[100:101], v[108:109]
	s_cbranch_vccnz .LBB0_1002
	v_cvt_pk_bf16_f32 v100, v20, v21
	v_cvt_pk_bf16_f32 v101, v22, v23
	global_store_dwordx2 v[80:81], v[100:101], off
	s_lshl_b64 s[26:27], s[20:21], 12
	v_lshl_add_u64 v[100:101], v[70:71], 0, s[26:27]
	s_cbranch_execnz .LBB0_972

.LBB0_981:
	s_and_b64 vcc, exec, s[12:13]
	s_cbranch_vccz .LBB0_907
	v_mul_f32_e32 v17, v17, v17
	v_fmac_f32_e32 v17, v16, v16
	v_mul_f32_e32 v16, v19, v19
	v_fmac_f32_e32 v16, v18, v18
	v_add_f32_e32 v16, v17, v16
	v_mul_f32_e32 v17, v25, v25
	v_mul_f32_e32 v18, v27, v27
	v_fmac_f32_e32 v17, v24, v24
	v_fmac_f32_e32 v18, v26, v26
	v_add_f32_e32 v17, v17, v18
	v_add_f32_e32 v16, v16, v17
	v_mul_f32_e32 v17, v29, v29
	v_mul_f32_e32 v18, v31, v31
	v_fmac_f32_e32 v17, v28, v28
	v_fmac_f32_e32 v18, v30, v30
	v_add_f32_e32 v17, v17, v18
	v_add_f32_e32 v16, v17, v16
	v_mul_f32_e32 v17, v33, v33
	v_mul_f32_e32 v18, v35, v35
	v_fmac_f32_e32 v17, v32, v32
	v_fmac_f32_e32 v18, v34, v34
	v_add_f32_e32 v17, v17, v18
	v_add_f32_e32 v16, v17, v16
	s_waitcnt lgkmcnt(0)
	s_nop 1
	v_add_f32_dpp v16, v16, v16 quad_perm:[1,0,3,2] row_mask:0xf bank_mask:0xf
	s_waitcnt lgkmcnt(0)
	s_nop 1
	v_add_f32_dpp v16, v16, v16 quad_perm:[2,3,0,1] row_mask:0xf bank_mask:0xf
	s_waitcnt lgkmcnt(0)
	s_nop 1
	v_add_f32_dpp v16, v16, v16 row_half_mirror row_mask:0xf bank_mask:0xf
	s_waitcnt lgkmcnt(0)
	s_nop 1
	v_add_f32_dpp v16, v16, v16 row_mirror row_mask:0xf bank_mask:0xf
	s_waitcnt lgkmcnt(0)
	v_mov_b32_e32 v17, v16
	s_nop 1
	v_permlane16_swap_b32_e32 v17, v16
	s_nop 1
	v_add_f32_e32 v16, v17, v16
	v_mov_b32_e32 v17, v16
	s_nop 1
	v_permlane32_swap_b32_e32 v17, v16
	s_nop 1
	s_and_saveexec_b64 s[16:17], s[42:43]
	s_cbranch_execz .LBB0_984
	s_waitcnt lgkmcnt(0)
	v_add_f32_e32 v16, v16, v17
	v_fmamk_f32 v16, v16, 0x3a800000, v219
	v_cmp_gt_f32_e32 vcc, s35, v16
	v_mul_f32_e32 v17, 0x4b800000, v16
	s_lshl_b64 s[26:27], s[10:11], 2
	v_cndmask_b32_e32 v16, v16, v17, vcc
	v_rsq_f32_e32 v16, v16
	s_add_u32 s26, s70, s26
	s_addc_u32 s27, s71, s27
	v_mul_f32_e32 v17, 0x45800000, v16
	v_cndmask_b32_e32 v16, v16, v17, vcc
	global_store_dword v3, v16, s[26:27]
.LBB0_984:
	s_or_b64 exec, exec, s[16:17]
	v_mul_f32_e32 v16, v37, v37
	s_waitcnt lgkmcnt(0)
	v_mul_f32_e32 v17, v39, v39
	v_fmac_f32_e32 v16, v36, v36
	v_fmac_f32_e32 v17, v38, v38
	v_add_f32_e32 v16, v16, v17
	v_mul_f32_e32 v17, v41, v41
	v_mul_f32_e32 v18, v43, v43
	v_fmac_f32_e32 v17, v40, v40
	v_fmac_f32_e32 v18, v42, v42
	v_add_f32_e32 v17, v17, v18
	v_add_f32_e32 v16, v16, v17
	v_mul_f32_e32 v17, v45, v45
	v_mul_f32_e32 v18, v47, v47
	v_fmac_f32_e32 v17, v44, v44
	v_fmac_f32_e32 v18, v46, v46
	v_add_f32_e32 v17, v17, v18
	v_add_f32_e32 v16, v17, v16
	v_mul_f32_e32 v17, v49, v49
	v_mul_f32_e32 v18, v51, v51
	v_fmac_f32_e32 v17, v48, v48
	v_fmac_f32_e32 v18, v50, v50
	v_add_f32_e32 v17, v17, v18
	v_add_f32_e32 v16, v17, v16
	s_waitcnt lgkmcnt(0)
	s_nop 1
	v_add_f32_dpp v16, v16, v16 quad_perm:[1,0,3,2] row_mask:0xf bank_mask:0xf
	s_waitcnt lgkmcnt(0)
	s_nop 1
	v_add_f32_dpp v16, v16, v16 quad_perm:[2,3,0,1] row_mask:0xf bank_mask:0xf
	s_waitcnt lgkmcnt(0)
	s_nop 1
	v_add_f32_dpp v16, v16, v16 row_half_mirror row_mask:0xf bank_mask:0xf
	s_waitcnt lgkmcnt(0)
	s_nop 1
	v_add_f32_dpp v16, v16, v16 row_mirror row_mask:0xf bank_mask:0xf
	s_waitcnt lgkmcnt(0)
	v_mov_b32_e32 v17, v16
	s_nop 1
	v_permlane16_swap_b32_e32 v17, v16
	s_nop 1
	v_add_f32_e32 v16, v17, v16
	v_mov_b32_e32 v17, v16
	s_nop 1
	v_permlane32_swap_b32_e32 v17, v16
	s_nop 1
	s_and_saveexec_b64 s[16:17], s[42:43]
	s_cbranch_execz .LBB0_986
	s_waitcnt lgkmcnt(0)
	v_add_f32_e32 v16, v16, v17
	v_fmamk_f32 v16, v16, 0x3a800000, v219
	v_cmp_gt_f32_e32 vcc, s35, v16
	v_mul_f32_e32 v17, 0x4b800000, v16
	s_lshl_b64 s[22:23], s[22:23], 2
	v_cndmask_b32_e32 v16, v16, v17, vcc
	v_rsq_f32_e32 v16, v16
	s_add_u32 s22, s70, s22
	s_addc_u32 s23, s71, s23
	v_mul_f32_e32 v17, 0x45800000, v16
	v_cndmask_b32_e32 v16, v16, v17, vcc
	global_store_dword v3, v16, s[22:23]
.LBB0_986:
	s_or_b64 exec, exec, s[16:17]
	v_mul_f32_e32 v16, v53, v53
	s_waitcnt lgkmcnt(0)
	v_mul_f32_e32 v17, v55, v55
	v_fmac_f32_e32 v16, v52, v52
	v_fmac_f32_e32 v17, v54, v54
	v_add_f32_e32 v16, v16, v17
	v_mul_f32_e32 v17, v57, v57
	v_mul_f32_e32 v18, v59, v59
	v_fmac_f32_e32 v17, v56, v56
	v_fmac_f32_e32 v18, v58, v58
	v_add_f32_e32 v17, v17, v18
	v_add_f32_e32 v16, v16, v17
	v_mul_f32_e32 v17, v61, v61
	v_mul_f32_e32 v18, v63, v63
	v_fmac_f32_e32 v17, v60, v60
	v_fmac_f32_e32 v18, v62, v62
	v_add_f32_e32 v17, v17, v18
	v_add_f32_e32 v16, v17, v16
	v_mul_f32_e32 v17, v65, v65
	v_mul_f32_e32 v18, v67, v67
	v_fmac_f32_e32 v17, v64, v64
	v_fmac_f32_e32 v18, v66, v66
	v_add_f32_e32 v17, v17, v18
	v_add_f32_e32 v16, v17, v16
	s_waitcnt lgkmcnt(0)
	s_nop 1
	v_add_f32_dpp v16, v16, v16 quad_perm:[1,0,3,2] row_mask:0xf bank_mask:0xf
	s_waitcnt lgkmcnt(0)
	s_nop 1
	v_add_f32_dpp v16, v16, v16 quad_perm:[2,3,0,1] row_mask:0xf bank_mask:0xf
	s_waitcnt lgkmcnt(0)
	s_nop 1
	v_add_f32_dpp v16, v16, v16 row_half_mirror row_mask:0xf bank_mask:0xf
	s_waitcnt lgkmcnt(0)
	s_nop 1
	v_add_f32_dpp v16, v16, v16 row_mirror row_mask:0xf bank_mask:0xf
	s_waitcnt lgkmcnt(0)
	v_mov_b32_e32 v17, v16
	s_nop 1
	v_permlane16_swap_b32_e32 v17, v16
	s_nop 1
	v_add_f32_e32 v16, v17, v16
	v_mov_b32_e32 v17, v16
	s_nop 1
	v_permlane32_swap_b32_e32 v17, v16
	s_nop 1
	s_and_saveexec_b64 s[16:17], s[42:43]
	s_cbranch_execz .LBB0_988
	s_waitcnt lgkmcnt(0)
	v_add_f32_e32 v16, v16, v17
	v_fmamk_f32 v16, v16, 0x3a800000, v219
	v_cmp_gt_f32_e32 vcc, s35, v16
	v_mul_f32_e32 v17, 0x4b800000, v16
	s_lshl_b64 s[2:3], s[2:3], 2
	v_cndmask_b32_e32 v16, v16, v17, vcc
	v_rsq_f32_e32 v16, v16
	s_add_u32 s2, s70, s2
	s_addc_u32 s3, s71, s3
	v_mul_f32_e32 v17, 0x45800000, v16
	v_cndmask_b32_e32 v16, v16, v17, vcc
	global_store_dword v3, v16, s[2:3]
.LBB0_988:
	s_or_b64 exec, exec, s[16:17]
	v_mul_f32_e32 v13, v13, v13
	v_mul_f32_e32 v16, v21, v21
	s_waitcnt lgkmcnt(0)
	v_mul_f32_e32 v17, v23, v23
	v_fmac_f32_e32 v13, v12, v12
	v_mul_f32_e32 v12, v15, v15
	v_mul_f32_e32 v9, v9, v9
	v_fmac_f32_e32 v16, v20, v20
	v_fmac_f32_e32 v17, v22, v22
	v_fmac_f32_e32 v12, v14, v14
	v_fmac_f32_e32 v9, v8, v8
	v_mul_f32_e32 v8, v11, v11
	v_mul_f32_e32 v5, v5, v5
	v_add_f32_e32 v16, v16, v17
	v_add_f32_e32 v12, v13, v12
	v_fmac_f32_e32 v8, v10, v10
	v_fmac_f32_e32 v5, v4, v4
	v_mul_f32_e32 v4, v7, v7
	v_add_f32_e32 v12, v16, v12
	v_add_f32_e32 v8, v9, v8
	v_fmac_f32_e32 v4, v6, v6
	v_add_f32_e32 v8, v8, v12
	v_add_f32_e32 v4, v5, v4
	v_add_f32_e32 v4, v4, v8
	s_waitcnt lgkmcnt(0)
	s_nop 1
	v_add_f32_dpp v1, v4, v4 quad_perm:[1,0,3,2] row_mask:0xf bank_mask:0xf
	s_waitcnt lgkmcnt(0)
	s_nop 1
	v_add_f32_dpp v1, v1, v1 quad_perm:[2,3,0,1] row_mask:0xf bank_mask:0xf
	s_waitcnt lgkmcnt(0)
	s_nop 1
	v_add_f32_dpp v1, v1, v1 row_half_mirror row_mask:0xf bank_mask:0xf
	s_waitcnt lgkmcnt(0)
	s_nop 1
	v_add_f32_dpp v1, v1, v1 row_mirror row_mask:0xf bank_mask:0xf
	s_waitcnt lgkmcnt(0)
	v_mov_b32_e32 v4, v1
	s_nop 1
	v_permlane16_swap_b32_e32 v4, v1
	s_nop 1
	v_add_f32_e32 v1, v4, v1
	v_mov_b32_e32 v4, v1
	s_nop 1
	v_permlane32_swap_b32_e32 v4, v1
	s_nop 1
	s_and_saveexec_b64 s[2:3], s[42:43]
	s_cbranch_execz .LBB0_906
	s_waitcnt lgkmcnt(0)
	v_add_f32_e32 v1, v1, v4
	v_fmamk_f32 v1, v1, 0x3a800000, v219
	v_cmp_gt_f32_e32 vcc, s35, v1
	v_mul_f32_e32 v4, 0x4b800000, v1
	s_lshl_b64 s[16:17], s[20:21], 2
	v_cndmask_b32_e32 v1, v1, v4, vcc
	v_rsq_f32_e32 v1, v1
	s_add_u32 s16, s70, s16
	s_addc_u32 s17, s71, s17
	v_mul_f32_e32 v4, 0x45800000, v1
	v_cndmask_b32_e32 v1, v1, v4, vcc
	global_store_dword v3, v1, s[16:17]
	s_branch .LBB0_906

.LBB0_1010:
	v_lshl_add_u64 v[24:25], s[70:71], 0, v[0:1]
	s_waitcnt lgkmcnt(0)
	v_add_co_u32_e32 v4, vcc, 0xf501000, v24
	s_nop 1
	v_addc_co_u32_e32 v5, vcc, 0, v25, vcc
	v_add_co_u32_e32 v6, vcc, 0x5201000, v24
	s_nop 1
	v_addc_co_u32_e32 v7, vcc, 0, v25, vcc
	global_load_dwordx2 v[40:41], v[4:5], off offset:1024
	global_load_dwordx2 v[28:29], v[4:5], off offset:1536
	global_load_dwordx2 v[30:31], v[4:5], off offset:2048
	global_load_dwordx2 v[32:33], v[4:5], off offset:2560
	global_load_dwordx2 v[54:55], v[6:7], off offset:1024
	global_load_dwordx2 v[42:43], v[6:7], off offset:1536
	global_load_dwordx2 v[34:35], v[6:7], off offset:2048
	global_load_dwordx2 v[26:27], v[6:7], off offset:2560
	global_load_dwordx4 v[12:15], v[20:21], off
	global_load_dwordx4 v[16:19], v[20:21], off offset:1024
	global_load_dwordx4 v[8:11], v[20:21], off offset:2048
	s_nop 0
	global_load_dwordx4 v[4:7], v[20:21], off offset:3072
	s_waitcnt vmcnt(11)
	v_and_b32_e32 v58, 0xffff0000, v41
	v_lshlrev_b32_e32 v61, 16, v41
	v_and_b32_e32 v57, 0xffff0000, v40
	v_mov_b32_e32 v60, v58
	v_mul_f32_e32 v2, v61, v61
	v_lshlrev_b32_e32 v56, 16, v40
	v_pk_fma_f32 v[62:63], v[60:61], v[60:61], v[2:3] op_sel_hi:[1,1,0]
	s_waitcnt vmcnt(10)
	v_and_b32_e32 v44, 0xffff0000, v28
	v_lshlrev_b32_e32 v45, 16, v29
	v_mul_f32_e32 v2, v57, v57
	v_lshlrev_b32_e32 v46, 16, v28
	v_and_b32_e32 v47, 0xffff0000, v29
	v_pk_mul_f32 v[28:29], v[44:45], v[44:45]
	s_waitcnt vmcnt(9)
	v_and_b32_e32 v38, 0xffff0000, v31
	v_lshlrev_b32_e32 v39, 16, v31
	s_waitcnt vmcnt(8)
	v_lshlrev_b32_e32 v31, 16, v32
	v_pk_fma_f32 v[66:67], v[56:57], v[56:57], v[2:3] op_sel_hi:[1,1,0]
	v_pk_fma_f32 v[64:65], v[46:47], v[46:47], v[28:29]
	v_lshlrev_b32_e32 v36, 16, v30
	v_and_b32_e32 v37, 0xffff0000, v30
	v_and_b32_e32 v29, 0xffff0000, v32
	v_mov_b32_e32 v30, v66
	v_mov_b32_e32 v68, v62
	v_mov_b32_e32 v69, v31
	v_mul_f32_e32 v28, v29, v29
	v_pk_add_f32 v[62:63], v[66:67], v[62:63]
	v_pk_mul_f32 v[66:67], v[30:31], v[68:69]
	v_pk_add_f32 v[64:65], v[64:65], v[64:65] op_sel:[0,1] op_sel_hi:[1,0]
	v_mov_b32_e32 v63, v67
	v_mov_b32_e32 v65, v28
	v_mul_f32_e32 v2, v37, v37
	v_lshlrev_b32_e32 v32, 16, v33
	v_and_b32_e32 v33, 0xffff0000, v33
	v_pk_add_f32 v[62:63], v[62:63], v[64:65]
	v_pk_fma_f32 v[64:65], v[36:37], v[36:37], v[2:3] op_sel_hi:[1,1,0]
	v_mul_f32_e32 v2, v39, v39
	v_mul_f32_e32 v40, v32, v32
	v_mul_f32_e32 v59, v33, v33
	v_pk_fma_f32 v[66:67], v[38:39], v[38:39], v[2:3] op_sel_hi:[1,1,0]
	v_mov_b32_e32 v65, v59
	v_mov_b32_e32 v67, v40
	v_pk_add_f32 v[64:65], v[64:65], v[66:67]
	v_and_b32_e32 v59, s0, v41
	v_pk_add_f32 v[62:63], v[62:63], v[64:65]
	v_pk_mov_b32 v[58:59], v[60:61], v[58:59] op_sel:[1,0]
	v_add_f32_e32 v2, v62, v63
	s_cmpk_lt_i32 s10, 0x4000
	s_waitcnt vmcnt(7)
	v_lshlrev_b32_e32 v62, 16, v54
	v_and_b32_e32 v63, 0xffff0000, v54
	v_lshlrev_b32_e32 v54, 16, v55
	s_waitcnt lgkmcnt(0)
	s_nop 1
	v_add_f32_dpp v2, v2, v2 quad_perm:[1,0,3,2] row_mask:0xf bank_mask:0xf
	v_and_b32_e32 v55, 0xffff0000, v55
	s_cselect_b64 s[4:5], -1, 0
	s_waitcnt lgkmcnt(0)
	s_nop 1
	v_add_f32_dpp v2, v2, v2 quad_perm:[2,3,0,1] row_mask:0xf bank_mask:0xf
	s_waitcnt lgkmcnt(0)
	s_nop 1
	v_add_f32_dpp v2, v2, v2 row_half_mirror row_mask:0xf bank_mask:0xf
	s_waitcnt lgkmcnt(0)
	s_nop 1
	v_add_f32_dpp v2, v2, v2 row_mirror row_mask:0xf bank_mask:0xf
	s_waitcnt lgkmcnt(0)
	v_mov_b32_e32 v28, v2
	s_nop 1
	v_permlane16_swap_b32_e32 v28, v2
	s_nop 1
	v_add_f32_e32 v2, v28, v2
	s_waitcnt lgkmcnt(0)
	v_mov_b32_e32 v28, v2
	s_nop 1
	v_permlane32_swap_b32_e32 v28, v2
	s_nop 1
	v_add_f32_e32 v2, v28, v2
	v_fmamk_f32 v2, v2, 0x3a800000, v219
	v_mul_f32_e32 v28, 0x4b800000, v2
	v_cmp_gt_f32_e32 vcc, s35, v2
	s_nop 1
	v_cndmask_b32_e32 v2, v2, v28, vcc
	v_rsq_f32_e32 v2, v2
	s_nop 0
	v_mul_f32_e32 v28, 0x45800000, v2
	v_cndmask_b32_e32 v40, v2, v28, vcc
	v_pk_mul_f32 v[56:57], v[40:41], v[56:57] op_sel_hi:[0,1]
	v_pk_mul_f32 v[58:59], v[40:41], v[58:59] op_sel_hi:[0,1]
	s_waitcnt vmcnt(3)
	v_pk_fma_f32 v[14:15], v[14:15], v[58:59], v[54:55]
	v_pk_fma_f32 v[12:13], v[12:13], v[56:57], v[62:63]
	s_and_b64 vcc, exec, s[12:13]
	s_cbranch_vccz .LBB0_1012
	v_lshl_add_u64 v[54:55], v[24:25], 0, s[48:49]
	v_cvt_pk_bf16_f32 v56, v12, v13
	v_cvt_pk_bf16_f32 v57, v14, v15
	global_store_dwordx2 v[54:55], v[56:57], off
	v_cndmask_b32_e64 v2, 0, 1, s[4:5]
	v_cmp_ne_u32_e64 s[48:49], 1, v2
	s_cbranch_execz .LBB0_1013
	s_branch .LBB0_1015

.LBB0_1030:
	s_and_b64 vcc, exec, s[12:13]
	s_mov_b64 s[48:49], 0x5201400
	s_cbranch_vccz .LBB0_1009
	v_mul_f32_e32 v2, v13, v13
	v_fmac_f32_e32 v2, v12, v12
	v_mul_f32_e32 v12, v14, v14
	v_fmac_f32_e32 v12, v15, v15
	v_add_f32_e32 v2, v2, v12
	v_mul_f32_e32 v12, v17, v17
	v_mul_f32_e32 v13, v18, v18
	v_mul_f32_e32 v9, v9, v9
	v_fmac_f32_e32 v12, v16, v16
	v_fmac_f32_e32 v13, v19, v19
	v_fmac_f32_e32 v9, v8, v8
	v_mul_f32_e32 v8, v10, v10
	v_mul_f32_e32 v5, v5, v5
	v_add_f32_e32 v12, v12, v13
	v_fmac_f32_e32 v8, v11, v11
	v_fmac_f32_e32 v5, v4, v4
	v_mul_f32_e32 v4, v6, v6
	v_add_f32_e32 v2, v2, v12
	v_add_f32_e32 v8, v9, v8
	v_fmac_f32_e32 v4, v7, v7
	v_add_f32_e32 v2, v8, v2
	v_add_f32_e32 v4, v5, v4
	v_add_f32_e32 v2, v4, v2
	s_waitcnt lgkmcnt(0)
	s_nop 1
	v_add_f32_dpp v2, v2, v2 quad_perm:[1,0,3,2] row_mask:0xf bank_mask:0xf
	s_waitcnt lgkmcnt(0)
	s_nop 1
	v_add_f32_dpp v2, v2, v2 quad_perm:[2,3,0,1] row_mask:0xf bank_mask:0xf
	s_waitcnt lgkmcnt(0)
	s_nop 1
	v_add_f32_dpp v2, v2, v2 row_half_mirror row_mask:0xf bank_mask:0xf
	s_waitcnt lgkmcnt(0)
	s_nop 1
	v_add_f32_dpp v2, v2, v2 row_mirror row_mask:0xf bank_mask:0xf
	s_waitcnt lgkmcnt(0)
	v_mov_b32_e32 v4, v2
	s_nop 1
	v_permlane16_swap_b32_e32 v4, v2
	s_nop 1
	v_add_f32_e32 v2, v4, v2
	v_mov_b32_e32 v4, v2
	s_nop 1
	v_permlane32_swap_b32_e32 v4, v2
	s_nop 1
	s_and_saveexec_b64 s[4:5], s[46:47]
	s_cbranch_execz .LBB0_1008
	s_waitcnt lgkmcnt(0)
	v_add_f32_e32 v2, v2, v4
	v_fmamk_f32 v2, v2, 0x3a800000, v219
	v_mul_f32_e32 v4, 0x4b800000, v2
	v_cmp_gt_f32_e32 vcc, s35, v2
	s_add_u32 s8, s70, s2
	s_addc_u32 s9, s71, s3
	v_cndmask_b32_e32 v2, v2, v4, vcc
	v_rsq_f32_e32 v2, v2
	s_nop 0
	v_mul_f32_e32 v4, 0x45800000, v2
	v_cndmask_b32_e32 v2, v2, v4, vcc
	global_store_dword v3, v2, s[8:9]
	s_branch .LBB0_1008

.LBB0_1247:
	v_lshl_add_u64 v[24:25], s[70:71], 0, v[22:23]
	v_add_co_u32_e32 v4, vcc, 0xf501000, v24
	s_waitcnt lgkmcnt(0)
	s_nop 0
	v_addc_co_u32_e32 v5, vcc, 0, v25, vcc
	v_add_co_u32_e32 v6, vcc, 0x5201000, v24
	s_nop 1
	v_addc_co_u32_e32 v7, vcc, 0, v25, vcc
	global_load_dwordx2 v[40:41], v[4:5], off offset:1024
	global_load_dwordx2 v[28:29], v[4:5], off offset:1536
	global_load_dwordx2 v[30:31], v[4:5], off offset:2048
	global_load_dwordx2 v[32:33], v[4:5], off offset:2560
	global_load_dwordx2 v[54:55], v[6:7], off offset:1024
	global_load_dwordx2 v[42:43], v[6:7], off offset:1536
	global_load_dwordx2 v[34:35], v[6:7], off offset:2048
	global_load_dwordx2 v[26:27], v[6:7], off offset:2560
	global_load_dwordx4 v[12:15], v[68:69], off
	global_load_dwordx4 v[16:19], v[68:69], off offset:1024
	global_load_dwordx4 v[8:11], v[68:69], off offset:2048
	s_nop 0
	global_load_dwordx4 v[4:7], v[68:69], off offset:3072
	s_waitcnt vmcnt(10)
	v_and_b32_e32 v44, 0xffff0000, v28
	v_lshlrev_b32_e32 v45, 16, v29
	v_and_b32_e32 v57, 0xffff0000, v40
	v_and_b32_e32 v58, 0xffff0000, v41
	v_lshlrev_b32_e32 v61, 16, v41
	v_lshlrev_b32_e32 v46, 16, v28
	v_and_b32_e32 v47, 0xffff0000, v29
	v_pk_mul_f32 v[28:29], v[44:45], v[44:45]
	v_lshlrev_b32_e32 v56, 16, v40
	v_mov_b32_e32 v60, v58
	v_mul_f32_e32 v36, v61, v61
	v_pk_fma_f32 v[64:65], v[46:47], v[46:47], v[28:29]
	s_waitcnt vmcnt(8)
	v_and_b32_e32 v29, 0xffff0000, v32
	v_mul_f32_e32 v28, v57, v57
	v_pk_fma_f32 v[62:63], v[60:61], v[60:61], v[36:37] op_sel_hi:[1,1,0]
	v_and_b32_e32 v38, 0xffff0000, v31
	v_lshlrev_b32_e32 v39, 16, v31
	v_lshlrev_b32_e32 v31, 16, v32
	v_pk_fma_f32 v[66:67], v[56:57], v[56:57], v[28:29] op_sel_hi:[1,1,0]
	v_lshlrev_b32_e32 v36, 16, v30
	v_and_b32_e32 v37, 0xffff0000, v30
	v_mov_b32_e32 v30, v66
	v_mov_b32_e32 v80, v62
	v_mov_b32_e32 v81, v31
	v_mul_f32_e32 v40, v29, v29
	v_pk_add_f32 v[62:63], v[66:67], v[62:63]
	v_pk_mul_f32 v[66:67], v[30:31], v[80:81]
	v_pk_add_f32 v[64:65], v[64:65], v[64:65] op_sel:[0,1] op_sel_hi:[1,0]
	v_mov_b32_e32 v63, v67
	v_mov_b32_e32 v65, v40
	v_mul_f32_e32 v28, v37, v37
	v_lshlrev_b32_e32 v32, 16, v33
	v_and_b32_e32 v33, 0xffff0000, v33
	v_pk_add_f32 v[62:63], v[62:63], v[64:65]
	v_pk_fma_f32 v[64:65], v[36:37], v[36:37], v[28:29] op_sel_hi:[1,1,0]
	v_mul_f32_e32 v28, v39, v39
	v_mul_f32_e32 v53, v32, v32
	v_mul_f32_e32 v59, v33, v33
	v_pk_fma_f32 v[66:67], v[38:39], v[38:39], v[28:29] op_sel_hi:[1,1,0]
	v_mov_b32_e32 v65, v59
	v_mov_b32_e32 v67, v53
	v_pk_add_f32 v[64:65], v[64:65], v[66:67]
	v_and_b32_e32 v59, s0, v41
	v_pk_add_f32 v[62:63], v[62:63], v[64:65]
	v_pk_mov_b32 v[58:59], v[60:61], v[58:59] op_sel:[1,0]
	v_add_f32_e32 v28, v62, v63
	s_waitcnt vmcnt(7)
	v_lshlrev_b32_e32 v62, 16, v54
	v_and_b32_e32 v63, 0xffff0000, v54
	v_lshlrev_b32_e32 v54, 16, v55
	v_and_b32_e32 v55, 0xffff0000, v55
	s_waitcnt lgkmcnt(0)
	s_nop 1
	v_add_f32_dpp v28, v28, v28 quad_perm:[1,0,3,2] row_mask:0xf bank_mask:0xf
	s_waitcnt lgkmcnt(0)
	s_nop 1
	v_add_f32_dpp v28, v28, v28 quad_perm:[2,3,0,1] row_mask:0xf bank_mask:0xf
	s_waitcnt lgkmcnt(0)
	s_nop 1
	v_add_f32_dpp v28, v28, v28 row_half_mirror row_mask:0xf bank_mask:0xf
	s_waitcnt lgkmcnt(0)
	s_nop 1
	v_add_f32_dpp v28, v28, v28 row_mirror row_mask:0xf bank_mask:0xf
	s_waitcnt lgkmcnt(0)
	v_mov_b32_e32 v30, v28
	s_nop 1
	v_permlane16_swap_b32_e32 v30, v28
	s_nop 1
	v_add_f32_e32 v28, v30, v28
	s_waitcnt lgkmcnt(0)
	v_mov_b32_e32 v30, v28
	s_nop 1
	v_permlane32_swap_b32_e32 v30, v28
	s_nop 1
	v_add_f32_e32 v28, v30, v28
	v_fmamk_f32 v28, v28, 0x3a800000, v219
	v_mul_f32_e32 v30, 0x4b800000, v28
	v_cmp_gt_f32_e32 vcc, s35, v28
	s_nop 1
	v_cndmask_b32_e32 v28, v28, v30, vcc
	v_rsq_f32_e32 v28, v28
	s_nop 0
	v_mul_f32_e32 v30, 0x45800000, v28
	v_cndmask_b32_e32 v40, v28, v30, vcc
	v_pk_mul_f32 v[56:57], v[40:41], v[56:57] op_sel_hi:[0,1]
	v_pk_mul_f32 v[58:59], v[40:41], v[58:59] op_sel_hi:[0,1]
	s_waitcnt vmcnt(3)
	v_pk_fma_f32 v[14:15], v[14:15], v[58:59], v[54:55]
	v_pk_fma_f32 v[12:13], v[12:13], v[56:57], v[62:63]
	s_and_b64 vcc, exec, s[6:7]
	s_cbranch_vccz .LBB0_1262
	v_lshl_add_u64 v[54:55], v[24:25], 0, s[48:49]
	v_cvt_pk_bf16_f32 v56, v12, v13
	v_cvt_pk_bf16_f32 v57, v14, v15
	global_store_dwordx2 v[54:55], v[56:57], off
	s_cbranch_execnz .LBB0_1250

.LBB0_1259:
	s_and_b64 vcc, exec, s[6:7]
	s_cbranch_vccz .LBB0_1246
	v_mul_f32_e32 v13, v13, v13
	v_fmac_f32_e32 v13, v12, v12
	v_mul_f32_e32 v12, v14, v14
	v_fmac_f32_e32 v12, v15, v15
	v_add_f32_e32 v12, v13, v12
	v_mul_f32_e32 v13, v17, v17
	v_mul_f32_e32 v14, v18, v18
	v_mul_f32_e32 v9, v9, v9
	v_fmac_f32_e32 v13, v16, v16
	v_fmac_f32_e32 v14, v19, v19
	v_fmac_f32_e32 v9, v8, v8
	v_mul_f32_e32 v8, v10, v10
	v_mul_f32_e32 v5, v5, v5
	v_add_f32_e32 v13, v13, v14
	v_fmac_f32_e32 v8, v11, v11
	v_fmac_f32_e32 v5, v4, v4
	v_mul_f32_e32 v4, v6, v6
	v_add_f32_e32 v12, v12, v13
	v_add_f32_e32 v8, v9, v8
	v_fmac_f32_e32 v4, v7, v7
	v_add_f32_e32 v8, v8, v12
	v_add_f32_e32 v4, v5, v4
	v_add_f32_e32 v4, v4, v8
	s_waitcnt lgkmcnt(0)
	s_nop 1
	v_add_f32_dpp v4, v4, v4 quad_perm:[1,0,3,2] row_mask:0xf bank_mask:0xf
	s_waitcnt lgkmcnt(0)
	s_nop 1
	v_add_f32_dpp v4, v4, v4 quad_perm:[2,3,0,1] row_mask:0xf bank_mask:0xf
	s_waitcnt lgkmcnt(0)
	s_nop 1
	v_add_f32_dpp v4, v4, v4 row_half_mirror row_mask:0xf bank_mask:0xf
	s_waitcnt lgkmcnt(0)
	s_nop 1
	v_add_f32_dpp v4, v4, v4 row_mirror row_mask:0xf bank_mask:0xf
	s_waitcnt lgkmcnt(0)
	v_mov_b32_e32 v5, v4
	s_nop 1
	v_permlane16_swap_b32_e32 v5, v4
	s_nop 1
	v_add_f32_e32 v4, v5, v4
	v_mov_b32_e32 v5, v4
	s_nop 1
	v_permlane32_swap_b32_e32 v5, v4
	s_nop 1
	s_and_saveexec_b64 s[16:17], s[38:39]
	s_cbranch_execz .LBB0_1245
	s_waitcnt lgkmcnt(0)
	v_add_f32_e32 v4, v4, v5
	v_fmamk_f32 v4, v4, 0x3a800000, v219
	v_mul_f32_e32 v5, 0x4b800000, v4
	v_cmp_gt_f32_e32 vcc, s35, v4
	s_add_u32 s22, s70, s2
	s_addc_u32 s23, s71, s3
	v_cndmask_b32_e32 v4, v4, v5, vcc
	v_rsq_f32_e32 v4, v4
	s_nop 0
	v_mul_f32_e32 v5, 0x45800000, v4
	v_cndmask_b32_e32 v4, v4, v5, vcc
	global_store_dword v3, v4, s[22:23]
	s_branch .LBB0_1245

.LBB0_1267:
	s_and_b64 vcc, exec, s[2:3]
	s_cbranch_vccz .LBB0_1242
	s_ashr_i32 s11, s10, 31
	s_sub_i32 s22, s20, s86
	s_lshl_b64 s[2:3], s[10:11], 11
	s_ashr_i32 s23, s22, 31
	s_waitcnt lgkmcnt(0)
	v_lshl_add_u64 v[4:5], v[72:73], 0, s[2:3]
	v_lshl_add_u64 v[102:103], v[74:75], 0, s[2:3]
	s_lshl_b64 s[2:3], s[22:23], 11
	global_load_dwordx2 v[16:17], v[4:5], off
	global_load_dwordx2 v[18:19], v[4:5], off offset:512
	global_load_dwordx2 v[34:35], v[4:5], off offset:1024
	global_load_dwordx2 v[104:105], v[4:5], off offset:1536
	global_load_dwordx2 v[108:109], v[102:103], off
	global_load_dwordx2 v[24:25], v[102:103], off offset:512
	global_load_dwordx2 v[28:29], v[102:103], off offset:1024
	global_load_dwordx2 v[32:33], v[102:103], off offset:1536
	v_lshl_add_u64 v[4:5], v[72:73], 0, s[2:3]
	v_lshl_add_u64 v[100:101], v[74:75], 0, s[2:3]
	s_add_i32 s2, s22, s90
	s_ashr_i32 s3, s2, 31
	s_lshl_b64 s[16:17], s[2:3], 11
	s_ashr_i32 s21, s20, 31
	global_load_dwordx2 v[50:51], v[4:5], off
	global_load_dwordx2 v[46:47], v[4:5], off offset:512
	global_load_dwordx2 v[42:43], v[4:5], off offset:1024
	global_load_dwordx2 v[38:39], v[4:5], off offset:1536
	global_load_dwordx2 v[36:37], v[100:101], off
	global_load_dwordx2 v[40:41], v[100:101], off offset:512
	global_load_dwordx2 v[44:45], v[100:101], off offset:1024
	global_load_dwordx2 v[48:49], v[100:101], off offset:1536
	v_lshl_add_u64 v[4:5], v[72:73], 0, s[16:17]
	v_lshl_add_u64 v[98:99], v[74:75], 0, s[16:17]
	s_lshl_b64 s[16:17], s[20:21], 11
	global_load_dwordx2 v[66:67], v[4:5], off
	global_load_dwordx2 v[62:63], v[4:5], off offset:512
	global_load_dwordx2 v[58:59], v[4:5], off offset:1024
	global_load_dwordx2 v[54:55], v[4:5], off offset:1536
	global_load_dwordx2 v[52:53], v[98:99], off
	global_load_dwordx2 v[56:57], v[98:99], off offset:512
	global_load_dwordx2 v[60:61], v[98:99], off offset:1024
	global_load_dwordx2 v[64:65], v[98:99], off offset:1536
	v_lshl_add_u64 v[4:5], v[72:73], 0, s[16:17]
	v_lshl_add_u64 v[80:81], v[74:75], 0, s[16:17]
	global_load_dwordx2 v[96:97], v[4:5], off
	global_load_dwordx2 v[94:95], v[4:5], off offset:512
	global_load_dwordx2 v[92:93], v[4:5], off offset:1024
	global_load_dwordx2 v[90:91], v[4:5], off offset:1536
	global_load_dwordx2 v[88:89], v[80:81], off
	global_load_dwordx2 v[86:87], v[80:81], off offset:512
	global_load_dwordx2 v[84:85], v[80:81], off offset:1024
	global_load_dwordx2 v[82:83], v[80:81], off offset:1536
	global_load_dwordx4 v[20:23], v[68:69], off
	global_load_dwordx4 v[12:15], v[68:69], off offset:1024
	global_load_dwordx4 v[8:11], v[68:69], off offset:2048
	global_load_dwordx4 v[4:7], v[68:69], off offset:3072
	v_and_b32_e32 v26, 64, v217
	s_waitcnt vmcnt(35)
	v_lshlrev_b32_e32 v110, 16, v16
	v_and_b32_e32 v111, 0xffff0000, v16
	v_lshlrev_b32_e32 v16, 16, v17
	v_and_b32_e32 v17, 0xffff0000, v17
	v_add_u32_e32 v124, 64, v26
	v_mul_f32_e32 v26, v17, v17
	s_waitcnt vmcnt(34)
	v_and_b32_e32 v113, 0xffff0000, v19
	v_and_b32_e32 v112, 0xffff0000, v18
	v_mul_f32_e32 v118, v111, v111
	v_pk_fma_f32 v[114:115], v[16:17], v[16:17], v[26:27] op_sel_hi:[1,1,0]
	v_lshlrev_b32_e32 v27, 16, v19
	v_lshlrev_b32_e32 v26, 16, v18
	v_pk_mul_f32 v[18:19], v[112:113], v[112:113]
	s_waitcnt vmcnt(33)
	v_lshlrev_b32_e32 v30, 16, v34
	v_and_b32_e32 v31, 0xffff0000, v34
	s_waitcnt vmcnt(32)
	v_lshlrev_b32_e32 v34, 16, v104
	v_pk_fma_f32 v[118:119], v[110:111], v[110:111], v[118:119] op_sel_hi:[1,1,0]
	v_pk_fma_f32 v[18:19], v[26:27], v[26:27], v[18:19]
	v_lshlrev_b32_e32 v106, 16, v35
	v_and_b32_e32 v107, 0xffff0000, v35
	v_and_b32_e32 v35, 0xffff0000, v104
	v_mov_b32_e32 v120, v118
	v_mov_b32_e32 v121, v34
	v_mov_b32_e32 v122, v114
	v_mov_b32_e32 v123, v34
	v_mul_f32_e32 v117, v35, v35
	v_pk_add_f32 v[114:115], v[118:119], v[114:115]
	v_pk_mul_f32 v[118:119], v[120:121], v[122:123]
	v_pk_add_f32 v[18:19], v[18:19], v[18:19] op_sel:[0,1] op_sel_hi:[1,0]
	v_mov_b32_e32 v115, v119
	v_mov_b32_e32 v19, v117
	v_lshlrev_b32_e32 v104, 16, v105
	v_and_b32_e32 v105, 0xffff0000, v105
	v_pk_add_f32 v[18:19], v[114:115], v[18:19]
	v_mul_f32_e32 v114, v31, v31
	v_mul_f32_e32 v118, v107, v107
	v_mul_f32_e32 v125, v104, v104
	v_mul_f32_e32 v126, v105, v105
	v_pk_fma_f32 v[114:115], v[30:31], v[30:31], v[114:115] op_sel_hi:[1,1,0]
	v_pk_fma_f32 v[118:119], v[106:107], v[106:107], v[118:119] op_sel_hi:[1,1,0]
	v_xor_b32_e32 v1, 1, v217
	v_mov_b32_e32 v115, v125
	v_mov_b32_e32 v119, v126
	v_cmp_lt_i32_e32 vcc, v1, v124
	v_pk_add_f32 v[114:115], v[114:115], v[118:119]
	s_nop 0
	v_cndmask_b32_e32 v1, v217, v1, vcc
	v_pk_add_f32 v[18:19], v[18:19], v[114:115]
	v_lshlrev_b32_e32 v1, 2, v1
	v_add_f32_e32 v18, v18, v19
	v_xor_b32_e32 v114, 2, v217
	v_cmp_lt_i32_e32 vcc, v114, v124
	s_waitcnt vmcnt(31)
	v_and_b32_e32 v115, 0xffff0000, v108
	s_waitcnt lgkmcnt(0)
	s_nop 1
	v_add_f32_dpp v18, v18, v18 quad_perm:[1,0,3,2] row_mask:0xf bank_mask:0xf
	v_cndmask_b32_e32 v114, v217, v114, vcc
	v_lshlrev_b32_e32 v117, 2, v114
	v_xor_b32_e32 v114, 4, v217
	v_cmp_lt_i32_e32 vcc, v114, v124
	s_waitcnt lgkmcnt(0)
	s_nop 1
	v_add_f32_dpp v18, v18, v18 quad_perm:[2,3,0,1] row_mask:0xf bank_mask:0xf
	v_cndmask_b32_e32 v114, v217, v114, vcc
	v_lshlrev_b32_e32 v118, 2, v114
	v_xor_b32_e32 v114, 8, v217
	v_cmp_lt_i32_e32 vcc, v114, v124
	s_waitcnt lgkmcnt(0)
	s_nop 1
	v_add_f32_dpp v18, v18, v18 row_half_mirror row_mask:0xf bank_mask:0xf
	v_cndmask_b32_e32 v114, v217, v114, vcc
	v_lshlrev_b32_e32 v119, 2, v114
	v_xor_b32_e32 v114, 16, v217
	v_cmp_lt_i32_e32 vcc, v114, v124
	s_waitcnt lgkmcnt(0)
	s_nop 1
	v_add_f32_dpp v18, v18, v18 row_mirror row_mask:0xf bank_mask:0xf
	v_cndmask_b32_e32 v114, v217, v114, vcc
	v_lshlrev_b32_e32 v120, 2, v114
	v_xor_b32_e32 v114, 32, v217
	v_cmp_lt_i32_e32 vcc, v114, v124
	s_waitcnt lgkmcnt(0)
	v_mov_b32_e32 v19, v18
	s_nop 1
	v_permlane16_swap_b32_e32 v19, v18
	s_nop 1
	v_add_f32_e32 v18, v19, v18
	v_cndmask_b32_e32 v114, v217, v114, vcc
	v_lshlrev_b32_e32 v121, 2, v114
	v_lshlrev_b32_e32 v114, 16, v108
	s_waitcnt lgkmcnt(0)
	v_mov_b32_e32 v19, v18
	s_nop 1
	v_permlane32_swap_b32_e32 v19, v18
	s_nop 1
	v_add_f32_e32 v18, v19, v18
	v_fmamk_f32 v18, v18, 0x3a800000, v219
	v_mul_f32_e32 v19, 0x4b800000, v18
	v_cmp_gt_f32_e32 vcc, s35, v18
	s_nop 1
	v_cndmask_b32_e32 v18, v18, v19, vcc
	v_rsq_f32_e32 v122, v18
	v_lshlrev_b32_e32 v18, 16, v109
	v_and_b32_e32 v19, 0xffff0000, v109
	v_mul_f32_e32 v108, 0x45800000, v122
	v_cndmask_b32_e32 v108, v122, v108, vcc
	v_pk_mul_f32 v[110:111], v[108:109], v[110:111] op_sel_hi:[0,1]
	v_pk_mul_f32 v[16:17], v[108:109], v[16:17] op_sel_hi:[0,1]
	s_waitcnt vmcnt(3)
	v_pk_fma_f32 v[18:19], v[22:23], v[16:17], v[18:19]
	v_pk_fma_f32 v[16:17], v[20:21], v[110:111], v[114:115]
	s_and_b64 vcc, exec, s[6:7]
	s_cbranch_vccz .LBB0_1325
	v_cvt_pk_bf16_f32 v110, v16, v17
	v_cvt_pk_bf16_f32 v111, v18, v19
	global_store_dwordx2 v[102:103], v[110:111], off
	s_lshl_b64 s[26:27], s[10:11], 12
	v_lshl_add_u64 v[110:111], v[70:71], 0, s[26:27]
	s_cbranch_execnz .LBB0_1271

.LBB0_1280:
	v_and_b32_e32 v123, 0xffff0000, v51
	v_lshlrev_b32_e32 v110, 16, v50
	v_and_b32_e32 v111, 0xffff0000, v50
	v_lshlrev_b32_e32 v122, 16, v51
	v_mul_f32_e32 v50, v123, v123
	v_pk_fma_f32 v[108:109], v[122:123], v[122:123], v[50:51] op_sel_hi:[1,1,0]
	v_and_b32_e32 v115, 0xffff0000, v47
	v_and_b32_e32 v114, 0xffff0000, v46
	v_lshlrev_b32_e32 v103, 16, v38
	v_and_b32_e32 v51, 0xffff0000, v38
	v_mul_f32_e32 v38, v111, v111
	v_lshlrev_b32_e32 v113, 16, v47
	v_lshlrev_b32_e32 v112, 16, v46
	v_pk_mul_f32 v[46:47], v[114:115], v[114:115]
	v_lshlrev_b32_e32 v104, 16, v39
	v_and_b32_e32 v105, 0xffff0000, v39
	v_pk_fma_f32 v[38:39], v[110:111], v[110:111], v[38:39] op_sel_hi:[1,1,0]
	v_pk_fma_f32 v[124:125], v[112:113], v[112:113], v[46:47]
	v_lshlrev_b32_e32 v46, 16, v42
	v_and_b32_e32 v47, 0xffff0000, v42
	v_lshlrev_b32_e32 v106, 16, v43
	v_and_b32_e32 v107, 0xffff0000, v43
	v_mov_b32_e32 v102, v38
	v_mov_b32_e32 v42, v108
	v_mov_b32_e32 v43, v103
	v_pk_add_f32 v[38:39], v[38:39], v[108:109]
	v_pk_mul_f32 v[42:43], v[102:103], v[42:43]
	v_mul_f32_e32 v50, v51, v51
	v_mov_b32_e32 v39, v43
	v_pk_add_f32 v[42:43], v[124:125], v[124:125] op_sel:[0,1] op_sel_hi:[1,0]
	v_mul_f32_e32 v126, v104, v104
	v_mov_b32_e32 v43, v50
	v_pk_add_f32 v[38:39], v[38:39], v[42:43]
	v_mul_f32_e32 v42, v47, v47
	v_mul_f32_e32 v50, v107, v107
	v_mul_f32_e32 v127, v105, v105
	v_pk_fma_f32 v[42:43], v[46:47], v[46:47], v[42:43] op_sel_hi:[1,1,0]
	v_pk_fma_f32 v[108:109], v[106:107], v[106:107], v[50:51] op_sel_hi:[1,1,0]
	v_mov_b32_e32 v43, v126
	v_mov_b32_e32 v109, v127
	v_pk_add_f32 v[42:43], v[42:43], v[108:109]
	s_nop 0
	v_pk_add_f32 v[38:39], v[38:39], v[42:43]
	v_lshlrev_b32_e32 v42, 16, v36
	v_add_f32_e32 v38, v38, v39
	v_and_b32_e32 v43, 0xffff0000, v36
	v_lshlrev_b32_e32 v36, 16, v37
	v_and_b32_e32 v37, 0xffff0000, v37
	s_waitcnt lgkmcnt(0)
	s_nop 1
	v_add_f32_dpp v38, v38, v38 quad_perm:[1,0,3,2] row_mask:0xf bank_mask:0xf
	s_waitcnt lgkmcnt(0)
	s_nop 1
	v_add_f32_dpp v38, v38, v38 quad_perm:[2,3,0,1] row_mask:0xf bank_mask:0xf
	s_waitcnt lgkmcnt(0)
	s_nop 1
	v_add_f32_dpp v38, v38, v38 row_half_mirror row_mask:0xf bank_mask:0xf
	s_waitcnt lgkmcnt(0)
	s_nop 1
	v_add_f32_dpp v38, v38, v38 row_mirror row_mask:0xf bank_mask:0xf
	s_waitcnt lgkmcnt(0)
	v_mov_b32_e32 v39, v38
	s_nop 1
	v_permlane16_swap_b32_e32 v39, v38
	s_nop 1
	v_add_f32_e32 v38, v39, v38
	s_waitcnt lgkmcnt(0)
	v_mov_b32_e32 v39, v38
	s_nop 1
	v_permlane32_swap_b32_e32 v39, v38
	s_nop 1
	v_add_f32_e32 v38, v39, v38
	v_fmamk_f32 v38, v38, 0x3a800000, v219
	v_mul_f32_e32 v39, 0x4b800000, v38
	v_cmp_gt_f32_e32 vcc, s35, v38
	s_nop 1
	v_cndmask_b32_e32 v38, v38, v39, vcc
	v_rsq_f32_e32 v38, v38
	s_nop 0
	v_mul_f32_e32 v39, 0x45800000, v38
	v_cndmask_b32_e32 v108, v38, v39, vcc
	v_pk_mul_f32 v[110:111], v[108:109], v[110:111] op_sel_hi:[0,1]
	v_pk_mul_f32 v[38:39], v[108:109], v[122:123] op_sel_hi:[0,1]
	v_pk_fma_f32 v[38:39], v[22:23], v[38:39], v[36:37]
	s_and_b64 vcc, exec, s[40:41]
	v_pk_fma_f32 v[36:37], v[20:21], v[110:111], v[42:43]
	s_cbranch_vccnz .LBB0_1329
	v_cvt_pk_bf16_f32 v42, v36, v37
	v_cvt_pk_bf16_f32 v43, v38, v39
	global_store_dwordx2 v[100:101], v[42:43], off
	s_lshl_b64 s[26:27], s[22:23], 12
	v_lshl_add_u64 v[110:111], v[70:71], 0, s[26:27]
	s_cbranch_execnz .LBB0_1283

.LBB0_1292:
	v_and_b32_e32 v115, 0xffff0000, v67
	v_lshlrev_b32_e32 v108, 16, v66
	v_and_b32_e32 v109, 0xffff0000, v66
	v_lshlrev_b32_e32 v114, 16, v67
	v_mul_f32_e32 v66, v115, v115
	v_pk_fma_f32 v[106:107], v[114:115], v[114:115], v[66:67] op_sel_hi:[1,1,0]
	v_and_b32_e32 v113, 0xffff0000, v63
	v_and_b32_e32 v112, 0xffff0000, v62
	v_lshlrev_b32_e32 v101, 16, v54
	v_and_b32_e32 v67, 0xffff0000, v54
	v_mul_f32_e32 v54, v109, v109
	v_lshlrev_b32_e32 v111, 16, v63
	v_lshlrev_b32_e32 v110, 16, v62
	v_pk_mul_f32 v[62:63], v[112:113], v[112:113]
	v_lshlrev_b32_e32 v102, 16, v55
	v_and_b32_e32 v103, 0xffff0000, v55
	v_pk_fma_f32 v[54:55], v[108:109], v[108:109], v[54:55] op_sel_hi:[1,1,0]
	v_pk_fma_f32 v[122:123], v[110:111], v[110:111], v[62:63]
	v_lshlrev_b32_e32 v62, 16, v58
	v_and_b32_e32 v63, 0xffff0000, v58
	v_lshlrev_b32_e32 v104, 16, v59
	v_and_b32_e32 v105, 0xffff0000, v59
	v_mov_b32_e32 v100, v54
	v_mov_b32_e32 v58, v106
	v_mov_b32_e32 v59, v101
	v_pk_add_f32 v[54:55], v[54:55], v[106:107]
	v_pk_mul_f32 v[58:59], v[100:101], v[58:59]
	v_mul_f32_e32 v66, v67, v67
	v_mov_b32_e32 v55, v59
	v_pk_add_f32 v[58:59], v[122:123], v[122:123] op_sel:[0,1] op_sel_hi:[1,0]
	v_mul_f32_e32 v124, v102, v102
	v_mov_b32_e32 v59, v66
	v_pk_add_f32 v[54:55], v[54:55], v[58:59]
	v_mul_f32_e32 v58, v63, v63
	v_mul_f32_e32 v66, v105, v105
	v_mul_f32_e32 v125, v103, v103
	v_pk_fma_f32 v[58:59], v[62:63], v[62:63], v[58:59] op_sel_hi:[1,1,0]
	v_pk_fma_f32 v[106:107], v[104:105], v[104:105], v[66:67] op_sel_hi:[1,1,0]
	v_mov_b32_e32 v59, v124
	v_mov_b32_e32 v107, v125
	v_pk_add_f32 v[58:59], v[58:59], v[106:107]
	s_nop 0
	v_pk_add_f32 v[54:55], v[54:55], v[58:59]
	v_lshlrev_b32_e32 v58, 16, v52
	v_add_f32_e32 v54, v54, v55
	v_and_b32_e32 v59, 0xffff0000, v52
	v_lshlrev_b32_e32 v52, 16, v53
	v_and_b32_e32 v53, 0xffff0000, v53
	s_waitcnt lgkmcnt(0)
	s_nop 1
	v_add_f32_dpp v54, v54, v54 quad_perm:[1,0,3,2] row_mask:0xf bank_mask:0xf
	s_waitcnt lgkmcnt(0)
	s_nop 1
	v_add_f32_dpp v54, v54, v54 quad_perm:[2,3,0,1] row_mask:0xf bank_mask:0xf
	s_waitcnt lgkmcnt(0)
	s_nop 1
	v_add_f32_dpp v54, v54, v54 row_half_mirror row_mask:0xf bank_mask:0xf
	s_waitcnt lgkmcnt(0)
	s_nop 1
	v_add_f32_dpp v54, v54, v54 row_mirror row_mask:0xf bank_mask:0xf
	s_waitcnt lgkmcnt(0)
	v_mov_b32_e32 v55, v54
	s_nop 1
	v_permlane16_swap_b32_e32 v55, v54
	s_nop 1
	v_add_f32_e32 v54, v55, v54
	s_waitcnt lgkmcnt(0)
	v_mov_b32_e32 v55, v54
	s_nop 1
	v_permlane32_swap_b32_e32 v55, v54
	s_nop 1
	v_add_f32_e32 v54, v55, v54
	v_fmamk_f32 v54, v54, 0x3a800000, v219
	v_mul_f32_e32 v55, 0x4b800000, v54
	v_cmp_gt_f32_e32 vcc, s35, v54
	s_nop 1
	v_cndmask_b32_e32 v54, v54, v55, vcc
	v_rsq_f32_e32 v54, v54
	s_nop 0
	v_mul_f32_e32 v55, 0x45800000, v54
	v_cndmask_b32_e32 v106, v54, v55, vcc
	v_pk_mul_f32 v[108:109], v[106:107], v[108:109] op_sel_hi:[0,1]
	v_pk_mul_f32 v[54:55], v[106:107], v[114:115] op_sel_hi:[0,1]
	v_pk_fma_f32 v[54:55], v[22:23], v[54:55], v[52:53]
	s_and_b64 vcc, exec, s[40:41]
	v_pk_fma_f32 v[52:53], v[20:21], v[108:109], v[58:59]
	s_cbranch_vccnz .LBB0_1333
	v_cvt_pk_bf16_f32 v58, v52, v53
	v_cvt_pk_bf16_f32 v59, v54, v55
	global_store_dwordx2 v[98:99], v[58:59], off
	s_lshl_b64 s[26:27], s[2:3], 12
	v_lshl_add_u64 v[108:109], v[70:71], 0, s[26:27]
	s_cbranch_execnz .LBB0_1295

.LBB0_1304:
	v_and_b32_e32 v107, 0xffff0000, v97
	v_lshlrev_b32_e32 v100, 16, v96
	v_and_b32_e32 v101, 0xffff0000, v96
	v_lshlrev_b32_e32 v106, 16, v97
	v_mul_f32_e32 v96, v107, v107
	v_and_b32_e32 v105, 0xffff0000, v95
	v_and_b32_e32 v104, 0xffff0000, v94
	v_pk_fma_f32 v[108:109], v[106:107], v[106:107], v[96:97] op_sel_hi:[1,1,0]
	v_lshlrev_b32_e32 v103, 16, v95
	v_lshlrev_b32_e32 v102, 16, v94
	v_pk_mul_f32 v[94:95], v[104:105], v[104:105]
	v_lshlrev_b32_e32 v96, 16, v92
	v_and_b32_e32 v97, 0xffff0000, v92
	v_lshlrev_b32_e32 v98, 16, v93
	v_and_b32_e32 v99, 0xffff0000, v93
	v_and_b32_e32 v93, 0xffff0000, v90
	v_mul_f32_e32 v92, v101, v101
	v_pk_fma_f32 v[110:111], v[102:103], v[102:103], v[94:95]
	v_lshlrev_b32_e32 v95, 16, v90
	v_pk_fma_f32 v[112:113], v[100:101], v[100:101], v[92:93] op_sel_hi:[1,1,0]
	v_mov_b32_e32 v114, v108
	v_mov_b32_e32 v94, v112
	v_mov_b32_e32 v115, v95
	v_mul_f32_e32 v122, v93, v93
	v_pk_add_f32 v[108:109], v[112:113], v[108:109]
	v_pk_mul_f32 v[112:113], v[94:95], v[114:115]
	v_pk_add_f32 v[110:111], v[110:111], v[110:111] op_sel:[0,1] op_sel_hi:[1,0]
	v_mov_b32_e32 v109, v113
	v_mov_b32_e32 v111, v122
	v_mul_f32_e32 v92, v97, v97
	v_lshlrev_b32_e32 v90, 16, v91
	v_and_b32_e32 v91, 0xffff0000, v91
	v_pk_add_f32 v[108:109], v[108:109], v[110:111]
	v_pk_fma_f32 v[110:111], v[96:97], v[96:97], v[92:93] op_sel_hi:[1,1,0]
	v_mul_f32_e32 v92, v99, v99
	v_mul_f32_e32 v123, v90, v90
	v_mul_f32_e32 v124, v91, v91
	v_pk_fma_f32 v[112:113], v[98:99], v[98:99], v[92:93] op_sel_hi:[1,1,0]
	v_mov_b32_e32 v111, v123
	v_mov_b32_e32 v113, v124
	v_pk_add_f32 v[110:111], v[110:111], v[112:113]
	s_nop 0
	v_pk_add_f32 v[108:109], v[108:109], v[110:111]
	v_lshlrev_b32_e32 v110, 16, v89
	v_add_f32_e32 v92, v108, v109
	v_lshlrev_b32_e32 v108, 16, v88
	v_and_b32_e32 v109, 0xffff0000, v88
	v_and_b32_e32 v111, 0xffff0000, v89
	s_waitcnt lgkmcnt(0)
	s_nop 1
	v_add_f32_dpp v92, v92, v92 quad_perm:[1,0,3,2] row_mask:0xf bank_mask:0xf
	s_waitcnt lgkmcnt(0)
	s_nop 1
	v_add_f32_dpp v92, v92, v92 quad_perm:[2,3,0,1] row_mask:0xf bank_mask:0xf
	s_waitcnt lgkmcnt(0)
	s_nop 1
	v_add_f32_dpp v92, v92, v92 row_half_mirror row_mask:0xf bank_mask:0xf
	s_waitcnt lgkmcnt(0)
	s_nop 1
	v_add_f32_dpp v92, v92, v92 row_mirror row_mask:0xf bank_mask:0xf
	s_waitcnt lgkmcnt(0)
	v_mov_b32_e32 v94, v92
	s_nop 1
	v_permlane16_swap_b32_e32 v94, v92
	s_nop 1
	v_add_f32_e32 v92, v94, v92
	s_waitcnt lgkmcnt(0)
	v_mov_b32_e32 v94, v92
	s_nop 1
	v_permlane32_swap_b32_e32 v94, v92
	s_nop 1
	v_add_f32_e32 v92, v94, v92
	v_fmamk_f32 v92, v92, 0x3a800000, v219
	v_mul_f32_e32 v94, 0x4b800000, v92
	v_cmp_gt_f32_e32 vcc, s35, v92
	s_nop 1
	v_cndmask_b32_e32 v92, v92, v94, vcc
	v_rsq_f32_e32 v92, v92
	s_nop 0
	v_mul_f32_e32 v88, 0x45800000, v92
	v_cndmask_b32_e32 v88, v92, v88, vcc
	v_pk_mul_f32 v[100:101], v[88:89], v[100:101] op_sel_hi:[0,1]
	v_pk_mul_f32 v[106:107], v[88:89], v[106:107] op_sel_hi:[0,1]
	v_pk_fma_f32 v[22:23], v[22:23], v[106:107], v[110:111]
	s_and_b64 vcc, exec, s[40:41]
	v_pk_fma_f32 v[20:21], v[20:21], v[100:101], v[108:109]
	s_cbranch_vccnz .LBB0_1337
	v_cvt_pk_bf16_f32 v100, v20, v21
	v_cvt_pk_bf16_f32 v101, v22, v23
	global_store_dwordx2 v[80:81], v[100:101], off
	s_lshl_b64 s[26:27], s[20:21], 12
	v_lshl_add_u64 v[100:101], v[70:71], 0, s[26:27]
	s_cbranch_execnz .LBB0_1307

.LBB0_1316:
	s_and_b64 vcc, exec, s[6:7]
	s_cbranch_vccz .LBB0_1242
	v_mul_f32_e32 v17, v17, v17
	v_fmac_f32_e32 v17, v16, v16
	v_mul_f32_e32 v16, v19, v19
	v_fmac_f32_e32 v16, v18, v18
	v_add_f32_e32 v16, v17, v16
	v_mul_f32_e32 v17, v25, v25
	v_mul_f32_e32 v18, v27, v27
	v_fmac_f32_e32 v17, v24, v24
	v_fmac_f32_e32 v18, v26, v26
	v_add_f32_e32 v17, v17, v18
	v_add_f32_e32 v16, v16, v17
	v_mul_f32_e32 v17, v29, v29
	v_mul_f32_e32 v18, v31, v31
	v_fmac_f32_e32 v17, v28, v28
	v_fmac_f32_e32 v18, v30, v30
	v_add_f32_e32 v17, v17, v18
	v_add_f32_e32 v16, v17, v16
	v_mul_f32_e32 v17, v33, v33
	v_mul_f32_e32 v18, v35, v35
	v_fmac_f32_e32 v17, v32, v32
	v_fmac_f32_e32 v18, v34, v34
	v_add_f32_e32 v17, v17, v18
	v_add_f32_e32 v16, v17, v16
	s_waitcnt lgkmcnt(0)
	s_nop 1
	v_add_f32_dpp v16, v16, v16 quad_perm:[1,0,3,2] row_mask:0xf bank_mask:0xf
	s_waitcnt lgkmcnt(0)
	s_nop 1
	v_add_f32_dpp v16, v16, v16 quad_perm:[2,3,0,1] row_mask:0xf bank_mask:0xf
	s_waitcnt lgkmcnt(0)
	s_nop 1
	v_add_f32_dpp v16, v16, v16 row_half_mirror row_mask:0xf bank_mask:0xf
	s_waitcnt lgkmcnt(0)
	s_nop 1
	v_add_f32_dpp v16, v16, v16 row_mirror row_mask:0xf bank_mask:0xf
	s_waitcnt lgkmcnt(0)
	v_mov_b32_e32 v17, v16
	s_nop 1
	v_permlane16_swap_b32_e32 v17, v16
	s_nop 1
	v_add_f32_e32 v16, v17, v16
	v_mov_b32_e32 v17, v16
	s_nop 1
	v_permlane32_swap_b32_e32 v17, v16
	s_nop 1
	s_and_saveexec_b64 s[16:17], s[38:39]
	s_cbranch_execz .LBB0_1319
	s_waitcnt lgkmcnt(0)
	v_add_f32_e32 v16, v16, v17
	v_fmamk_f32 v16, v16, 0x3a800000, v219
	v_cmp_gt_f32_e32 vcc, s35, v16
	v_mul_f32_e32 v17, 0x4b800000, v16
	s_lshl_b64 s[26:27], s[10:11], 2
	v_cndmask_b32_e32 v16, v16, v17, vcc
	v_rsq_f32_e32 v16, v16
	s_add_u32 s26, s70, s26
	s_addc_u32 s27, s71, s27
	v_mul_f32_e32 v17, 0x45800000, v16
	v_cndmask_b32_e32 v16, v16, v17, vcc
	global_store_dword v3, v16, s[26:27]
.LBB0_1319:
	s_or_b64 exec, exec, s[16:17]
	v_mul_f32_e32 v16, v37, v37
	s_waitcnt lgkmcnt(0)
	v_mul_f32_e32 v17, v39, v39
	v_fmac_f32_e32 v16, v36, v36
	v_fmac_f32_e32 v17, v38, v38
	v_add_f32_e32 v16, v16, v17
	v_mul_f32_e32 v17, v41, v41
	v_mul_f32_e32 v18, v43, v43
	v_fmac_f32_e32 v17, v40, v40
	v_fmac_f32_e32 v18, v42, v42
	v_add_f32_e32 v17, v17, v18
	v_add_f32_e32 v16, v16, v17
	v_mul_f32_e32 v17, v45, v45
	v_mul_f32_e32 v18, v47, v47
	v_fmac_f32_e32 v17, v44, v44
	v_fmac_f32_e32 v18, v46, v46
	v_add_f32_e32 v17, v17, v18
	v_add_f32_e32 v16, v17, v16
	v_mul_f32_e32 v17, v49, v49
	v_mul_f32_e32 v18, v51, v51
	v_fmac_f32_e32 v17, v48, v48
	v_fmac_f32_e32 v18, v50, v50
	v_add_f32_e32 v17, v17, v18
	v_add_f32_e32 v16, v17, v16
	s_waitcnt lgkmcnt(0)
	s_nop 1
	v_add_f32_dpp v16, v16, v16 quad_perm:[1,0,3,2] row_mask:0xf bank_mask:0xf
	s_waitcnt lgkmcnt(0)
	s_nop 1
	v_add_f32_dpp v16, v16, v16 quad_perm:[2,3,0,1] row_mask:0xf bank_mask:0xf
	s_waitcnt lgkmcnt(0)
	s_nop 1
	v_add_f32_dpp v16, v16, v16 row_half_mirror row_mask:0xf bank_mask:0xf
	s_waitcnt lgkmcnt(0)
	s_nop 1
	v_add_f32_dpp v16, v16, v16 row_mirror row_mask:0xf bank_mask:0xf
	s_waitcnt lgkmcnt(0)
	v_mov_b32_e32 v17, v16
	s_nop 1
	v_permlane16_swap_b32_e32 v17, v16
	s_nop 1
	v_add_f32_e32 v16, v17, v16
	v_mov_b32_e32 v17, v16
	s_nop 1
	v_permlane32_swap_b32_e32 v17, v16
	s_nop 1
	s_and_saveexec_b64 s[16:17], s[38:39]
	s_cbranch_execz .LBB0_1321
	s_waitcnt lgkmcnt(0)
	v_add_f32_e32 v16, v16, v17
	v_fmamk_f32 v16, v16, 0x3a800000, v219
	v_cmp_gt_f32_e32 vcc, s35, v16
	v_mul_f32_e32 v17, 0x4b800000, v16
	s_lshl_b64 s[22:23], s[22:23], 2
	v_cndmask_b32_e32 v16, v16, v17, vcc
	v_rsq_f32_e32 v16, v16
	s_add_u32 s22, s70, s22
	s_addc_u32 s23, s71, s23
	v_mul_f32_e32 v17, 0x45800000, v16
	v_cndmask_b32_e32 v16, v16, v17, vcc
	global_store_dword v3, v16, s[22:23]
.LBB0_1321:
	s_or_b64 exec, exec, s[16:17]
	v_mul_f32_e32 v16, v53, v53
	s_waitcnt lgkmcnt(0)
	v_mul_f32_e32 v17, v55, v55
	v_fmac_f32_e32 v16, v52, v52
	v_fmac_f32_e32 v17, v54, v54
	v_add_f32_e32 v16, v16, v17
	v_mul_f32_e32 v17, v57, v57
	v_mul_f32_e32 v18, v59, v59
	v_fmac_f32_e32 v17, v56, v56
	v_fmac_f32_e32 v18, v58, v58
	v_add_f32_e32 v17, v17, v18
	v_add_f32_e32 v16, v16, v17
	v_mul_f32_e32 v17, v61, v61
	v_mul_f32_e32 v18, v63, v63
	v_fmac_f32_e32 v17, v60, v60
	v_fmac_f32_e32 v18, v62, v62
	v_add_f32_e32 v17, v17, v18
	v_add_f32_e32 v16, v17, v16
	v_mul_f32_e32 v17, v65, v65
	v_mul_f32_e32 v18, v67, v67
	v_fmac_f32_e32 v17, v64, v64
	v_fmac_f32_e32 v18, v66, v66
	v_add_f32_e32 v17, v17, v18
	v_add_f32_e32 v16, v17, v16
	s_waitcnt lgkmcnt(0)
	s_nop 1
	v_add_f32_dpp v16, v16, v16 quad_perm:[1,0,3,2] row_mask:0xf bank_mask:0xf
	s_waitcnt lgkmcnt(0)
	s_nop 1
	v_add_f32_dpp v16, v16, v16 quad_perm:[2,3,0,1] row_mask:0xf bank_mask:0xf
	s_waitcnt lgkmcnt(0)
	s_nop 1
	v_add_f32_dpp v16, v16, v16 row_half_mirror row_mask:0xf bank_mask:0xf
	s_waitcnt lgkmcnt(0)
	s_nop 1
	v_add_f32_dpp v16, v16, v16 row_mirror row_mask:0xf bank_mask:0xf
	s_waitcnt lgkmcnt(0)
	v_mov_b32_e32 v17, v16
	s_nop 1
	v_permlane16_swap_b32_e32 v17, v16
	s_nop 1
	v_add_f32_e32 v16, v17, v16
	v_mov_b32_e32 v17, v16
	s_nop 1
	v_permlane32_swap_b32_e32 v17, v16
	s_nop 1
	s_and_saveexec_b64 s[16:17], s[38:39]
	s_cbranch_execz .LBB0_1323
	s_waitcnt lgkmcnt(0)
	v_add_f32_e32 v16, v16, v17
	v_fmamk_f32 v16, v16, 0x3a800000, v219
	v_cmp_gt_f32_e32 vcc, s35, v16
	v_mul_f32_e32 v17, 0x4b800000, v16
	s_lshl_b64 s[2:3], s[2:3], 2
	v_cndmask_b32_e32 v16, v16, v17, vcc
	v_rsq_f32_e32 v16, v16
	s_add_u32 s2, s70, s2
	s_addc_u32 s3, s71, s3
	v_mul_f32_e32 v17, 0x45800000, v16
	v_cndmask_b32_e32 v16, v16, v17, vcc
	global_store_dword v3, v16, s[2:3]
.LBB0_1323:
	s_or_b64 exec, exec, s[16:17]
	v_mul_f32_e32 v13, v13, v13
	v_mul_f32_e32 v16, v21, v21
	s_waitcnt lgkmcnt(0)
	v_mul_f32_e32 v17, v23, v23
	v_fmac_f32_e32 v13, v12, v12
	v_mul_f32_e32 v12, v15, v15
	v_mul_f32_e32 v9, v9, v9
	v_fmac_f32_e32 v16, v20, v20
	v_fmac_f32_e32 v17, v22, v22
	v_fmac_f32_e32 v12, v14, v14
	v_fmac_f32_e32 v9, v8, v8
	v_mul_f32_e32 v8, v11, v11
	v_mul_f32_e32 v5, v5, v5
	v_add_f32_e32 v16, v16, v17
	v_add_f32_e32 v12, v13, v12
	v_fmac_f32_e32 v8, v10, v10
	v_fmac_f32_e32 v5, v4, v4
	v_mul_f32_e32 v4, v7, v7
	v_add_f32_e32 v12, v16, v12
	v_add_f32_e32 v8, v9, v8
	v_fmac_f32_e32 v4, v6, v6
	v_add_f32_e32 v8, v8, v12
	v_add_f32_e32 v4, v5, v4
	v_add_f32_e32 v4, v4, v8
	s_waitcnt lgkmcnt(0)
	s_nop 1
	v_add_f32_dpp v1, v4, v4 quad_perm:[1,0,3,2] row_mask:0xf bank_mask:0xf
	s_waitcnt lgkmcnt(0)
	s_nop 1
	v_add_f32_dpp v1, v1, v1 quad_perm:[2,3,0,1] row_mask:0xf bank_mask:0xf
	s_waitcnt lgkmcnt(0)
	s_nop 1
	v_add_f32_dpp v1, v1, v1 row_half_mirror row_mask:0xf bank_mask:0xf
	s_waitcnt lgkmcnt(0)
	s_nop 1
	v_add_f32_dpp v1, v1, v1 row_mirror row_mask:0xf bank_mask:0xf
	s_waitcnt lgkmcnt(0)
	v_mov_b32_e32 v4, v1
	s_nop 1
	v_permlane16_swap_b32_e32 v4, v1
	s_nop 1
	v_add_f32_e32 v1, v4, v1
	v_mov_b32_e32 v4, v1
	s_nop 1
	v_permlane32_swap_b32_e32 v4, v1
	s_nop 1
	s_and_saveexec_b64 s[2:3], s[38:39]
	s_cbranch_execz .LBB0_1241
	s_waitcnt lgkmcnt(0)
	v_add_f32_e32 v1, v1, v4
	v_fmamk_f32 v1, v1, 0x3a800000, v219
	v_cmp_gt_f32_e32 vcc, s35, v1
	v_mul_f32_e32 v4, 0x4b800000, v1
	s_lshl_b64 s[16:17], s[20:21], 2
	v_cndmask_b32_e32 v1, v1, v4, vcc
	v_rsq_f32_e32 v1, v1
	s_add_u32 s16, s70, s16
	s_addc_u32 s17, s71, s17
	v_mul_f32_e32 v4, 0x45800000, v1
	v_cndmask_b32_e32 v1, v1, v4, vcc
	global_store_dword v3, v1, s[16:17]
	s_branch .LBB0_1241

.LBB0_1345:
	v_lshl_add_u64 v[24:25], s[70:71], 0, v[0:1]
	s_waitcnt lgkmcnt(0)
	v_add_co_u32_e32 v4, vcc, 0xf501000, v24
	s_nop 1
	v_addc_co_u32_e32 v5, vcc, 0, v25, vcc
	v_add_co_u32_e32 v6, vcc, 0x5201000, v24
	s_nop 1
	v_addc_co_u32_e32 v7, vcc, 0, v25, vcc
	global_load_dwordx2 v[40:41], v[4:5], off offset:1024
	global_load_dwordx2 v[28:29], v[4:5], off offset:1536
	global_load_dwordx2 v[30:31], v[4:5], off offset:2048
	global_load_dwordx2 v[32:33], v[4:5], off offset:2560
	global_load_dwordx2 v[54:55], v[6:7], off offset:1024
	global_load_dwordx2 v[42:43], v[6:7], off offset:1536
	global_load_dwordx2 v[34:35], v[6:7], off offset:2048
	global_load_dwordx2 v[26:27], v[6:7], off offset:2560
	global_load_dwordx4 v[12:15], v[20:21], off
	global_load_dwordx4 v[16:19], v[20:21], off offset:1024
	global_load_dwordx4 v[8:11], v[20:21], off offset:2048
	s_nop 0
	global_load_dwordx4 v[4:7], v[20:21], off offset:3072
	s_waitcnt vmcnt(11)
	v_and_b32_e32 v58, 0xffff0000, v41
	v_lshlrev_b32_e32 v61, 16, v41
	v_and_b32_e32 v57, 0xffff0000, v40
	v_mov_b32_e32 v60, v58
	v_mul_f32_e32 v2, v61, v61
	v_lshlrev_b32_e32 v56, 16, v40
	v_pk_fma_f32 v[62:63], v[60:61], v[60:61], v[2:3] op_sel_hi:[1,1,0]
	s_waitcnt vmcnt(10)
	v_and_b32_e32 v44, 0xffff0000, v28
	v_lshlrev_b32_e32 v45, 16, v29
	v_mul_f32_e32 v2, v57, v57
	v_lshlrev_b32_e32 v46, 16, v28
	v_and_b32_e32 v47, 0xffff0000, v29
	v_pk_mul_f32 v[28:29], v[44:45], v[44:45]
	s_waitcnt vmcnt(9)
	v_and_b32_e32 v38, 0xffff0000, v31
	v_lshlrev_b32_e32 v39, 16, v31
	s_waitcnt vmcnt(8)
	v_lshlrev_b32_e32 v31, 16, v32
	v_pk_fma_f32 v[66:67], v[56:57], v[56:57], v[2:3] op_sel_hi:[1,1,0]
	v_pk_fma_f32 v[64:65], v[46:47], v[46:47], v[28:29]
	v_lshlrev_b32_e32 v36, 16, v30
	v_and_b32_e32 v37, 0xffff0000, v30
	v_and_b32_e32 v29, 0xffff0000, v32
	v_mov_b32_e32 v30, v66
	v_mov_b32_e32 v68, v62
	v_mov_b32_e32 v69, v31
	v_mul_f32_e32 v28, v29, v29
	v_pk_add_f32 v[62:63], v[66:67], v[62:63]
	v_pk_mul_f32 v[66:67], v[30:31], v[68:69]
	v_pk_add_f32 v[64:65], v[64:65], v[64:65] op_sel:[0,1] op_sel_hi:[1,0]
	v_mov_b32_e32 v63, v67
	v_mov_b32_e32 v65, v28
	v_mul_f32_e32 v2, v37, v37
	v_lshlrev_b32_e32 v32, 16, v33
	v_and_b32_e32 v33, 0xffff0000, v33
	v_pk_add_f32 v[62:63], v[62:63], v[64:65]
	v_pk_fma_f32 v[64:65], v[36:37], v[36:37], v[2:3] op_sel_hi:[1,1,0]
	v_mul_f32_e32 v2, v39, v39
	v_mul_f32_e32 v40, v32, v32
	v_mul_f32_e32 v59, v33, v33
	v_pk_fma_f32 v[66:67], v[38:39], v[38:39], v[2:3] op_sel_hi:[1,1,0]
	v_mov_b32_e32 v65, v59
	v_mov_b32_e32 v67, v40
	v_pk_add_f32 v[64:65], v[64:65], v[66:67]
	v_and_b32_e32 v59, s0, v41
	v_pk_add_f32 v[62:63], v[62:63], v[64:65]
	v_pk_mov_b32 v[58:59], v[60:61], v[58:59] op_sel:[1,0]
	v_add_f32_e32 v2, v62, v63
	s_cmpk_lt_i32 s8, 0x4000
	s_waitcnt vmcnt(7)
	v_lshlrev_b32_e32 v62, 16, v54
	v_and_b32_e32 v63, 0xffff0000, v54
	v_lshlrev_b32_e32 v54, 16, v55
	s_waitcnt lgkmcnt(0)
	s_nop 1
	v_add_f32_dpp v2, v2, v2 quad_perm:[1,0,3,2] row_mask:0xf bank_mask:0xf
	v_and_b32_e32 v55, 0xffff0000, v55
	s_cselect_b64 s[4:5], -1, 0
	s_waitcnt lgkmcnt(0)
	s_nop 1
	v_add_f32_dpp v2, v2, v2 quad_perm:[2,3,0,1] row_mask:0xf bank_mask:0xf
	s_waitcnt lgkmcnt(0)
	s_nop 1
	v_add_f32_dpp v2, v2, v2 row_half_mirror row_mask:0xf bank_mask:0xf
	s_waitcnt lgkmcnt(0)
	s_nop 1
	v_add_f32_dpp v2, v2, v2 row_mirror row_mask:0xf bank_mask:0xf
	s_waitcnt lgkmcnt(0)
	v_mov_b32_e32 v28, v2
	s_nop 1
	v_permlane16_swap_b32_e32 v28, v2
	s_nop 1
	v_add_f32_e32 v2, v28, v2
	s_waitcnt lgkmcnt(0)
	v_mov_b32_e32 v28, v2
	s_nop 1
	v_permlane32_swap_b32_e32 v28, v2
	s_nop 1
	v_add_f32_e32 v2, v28, v2
	v_fmamk_f32 v2, v2, 0x3a800000, v219
	v_mul_f32_e32 v28, 0x4b800000, v2
	v_cmp_gt_f32_e32 vcc, s35, v2
	s_nop 1
	v_cndmask_b32_e32 v2, v2, v28, vcc
	v_rsq_f32_e32 v2, v2
	s_nop 0
	v_mul_f32_e32 v28, 0x45800000, v2
	v_cndmask_b32_e32 v40, v2, v28, vcc
	v_pk_mul_f32 v[56:57], v[40:41], v[56:57] op_sel_hi:[0,1]
	v_pk_mul_f32 v[58:59], v[40:41], v[58:59] op_sel_hi:[0,1]
	s_waitcnt vmcnt(3)
	v_pk_fma_f32 v[14:15], v[14:15], v[58:59], v[54:55]
	v_pk_fma_f32 v[12:13], v[12:13], v[56:57], v[62:63]
	s_and_b64 vcc, exec, s[0:1]
	s_cbranch_vccz .LBB0_1347
	v_lshl_add_u64 v[54:55], v[24:25], 0, s[48:49]
	v_cvt_pk_bf16_f32 v56, v12, v13
	v_cvt_pk_bf16_f32 v57, v14, v15
	global_store_dwordx2 v[54:55], v[56:57], off
	v_cndmask_b32_e64 v2, 0, 1, s[4:5]
	v_cmp_ne_u32_e64 s[40:41], 1, v2
	s_cbranch_execz .LBB0_1348
	s_branch .LBB0_1350

.LBB0_1365:
	s_and_b64 vcc, exec, s[0:1]
	s_cbranch_vccz .LBB0_1344
	v_mul_f32_e32 v2, v13, v13
	v_fmac_f32_e32 v2, v12, v12
	v_mul_f32_e32 v12, v14, v14
	v_fmac_f32_e32 v12, v15, v15
	v_add_f32_e32 v2, v2, v12
	v_mul_f32_e32 v12, v17, v17
	v_mul_f32_e32 v13, v18, v18
	v_mul_f32_e32 v9, v9, v9
	v_fmac_f32_e32 v12, v16, v16
	v_fmac_f32_e32 v13, v19, v19
	v_fmac_f32_e32 v9, v8, v8
	v_mul_f32_e32 v8, v10, v10
	v_mul_f32_e32 v5, v5, v5
	v_add_f32_e32 v12, v12, v13
	v_fmac_f32_e32 v8, v11, v11
	v_fmac_f32_e32 v5, v4, v4
	v_mul_f32_e32 v4, v6, v6
	v_add_f32_e32 v2, v2, v12
	v_add_f32_e32 v8, v9, v8
	v_fmac_f32_e32 v4, v7, v7
	v_add_f32_e32 v2, v8, v2
	v_add_f32_e32 v4, v5, v4
	v_add_f32_e32 v2, v4, v2
	s_waitcnt lgkmcnt(0)
	s_nop 1
	v_add_f32_dpp v2, v2, v2 quad_perm:[1,0,3,2] row_mask:0xf bank_mask:0xf
	s_waitcnt lgkmcnt(0)
	s_nop 1
	v_add_f32_dpp v2, v2, v2 quad_perm:[2,3,0,1] row_mask:0xf bank_mask:0xf
	s_waitcnt lgkmcnt(0)
	s_nop 1
	v_add_f32_dpp v2, v2, v2 row_half_mirror row_mask:0xf bank_mask:0xf
	s_waitcnt lgkmcnt(0)
	s_nop 1
	v_add_f32_dpp v2, v2, v2 row_mirror row_mask:0xf bank_mask:0xf
	s_waitcnt lgkmcnt(0)
	v_mov_b32_e32 v4, v2
	s_nop 1
	v_permlane16_swap_b32_e32 v4, v2
	s_nop 1
	v_add_f32_e32 v2, v4, v2
	v_mov_b32_e32 v4, v2
	s_nop 1
	v_permlane32_swap_b32_e32 v4, v2
	s_nop 1
	s_and_saveexec_b64 s[4:5], s[38:39]
	s_cbranch_execz .LBB0_1343
	s_waitcnt lgkmcnt(0)
	v_add_f32_e32 v2, v2, v4
	v_fmamk_f32 v2, v2, 0x3a800000, v219
	v_mul_f32_e32 v4, 0x4b800000, v2
	v_cmp_gt_f32_e32 vcc, s35, v2
	s_add_u32 s6, s70, s2
	s_addc_u32 s7, s71, s3
	v_cndmask_b32_e32 v2, v2, v4, vcc
	v_rsq_f32_e32 v2, v2
	s_nop 0
	v_mul_f32_e32 v4, 0x45800000, v2
	v_cndmask_b32_e32 v2, v2, v4, vcc
	global_store_dword v3, v2, s[6:7]
	s_branch .LBB0_1343

.LBB0_1382:
	s_waitcnt lgkmcnt(0)
	global_load_dwordx4 v[10:13], v2, s[4:5]
	global_load_dwordx4 v[14:17], v2, s[4:5] offset:1024
	global_load_dwordx4 v[18:21], v2, s[4:5] offset:2048
	global_load_dwordx4 v[22:25], v2, s[4:5] offset:3072
	s_waitcnt vmcnt(3)
	v_mul_f32_e32 v26, v11, v11
	v_mul_f32_e32 v27, v13, v13
	v_fmac_f32_e32 v26, v10, v10
	v_fmac_f32_e32 v27, v12, v12
	v_add_f32_e32 v26, v26, v27
	s_waitcnt vmcnt(2)
	v_mul_f32_e32 v27, v15, v15
	v_mul_f32_e32 v28, v17, v17
	v_fmac_f32_e32 v27, v14, v14
	v_fmac_f32_e32 v28, v16, v16
	v_add_f32_e32 v27, v27, v28
	v_add_f32_e32 v26, v26, v27
	s_waitcnt vmcnt(1)
	v_mul_f32_e32 v27, v19, v19
	v_mul_f32_e32 v28, v21, v21
	v_fmac_f32_e32 v27, v18, v18
	v_fmac_f32_e32 v28, v20, v20
	v_add_f32_e32 v27, v27, v28
	v_add_f32_e32 v26, v26, v27
	s_waitcnt vmcnt(0)
	v_mul_f32_e32 v27, v23, v23
	v_mul_f32_e32 v28, v25, v25
	v_fmac_f32_e32 v27, v22, v22
	v_fmac_f32_e32 v28, v24, v24
	v_add_f32_e32 v27, v27, v28
	v_add_f32_e32 v26, v26, v27
	s_mov_b32 s4, 0x5201000
	v_cvt_pk_bf16_f32 v10, v10, v11
	v_cvt_pk_bf16_f32 v11, v12, v13
	s_waitcnt lgkmcnt(0)
	s_nop 1
	v_add_f32_dpp v28, v26, v26 quad_perm:[1,0,3,2] row_mask:0xf bank_mask:0xf
	v_lshl_add_u64 v[26:27], s[70:71], 0, v[0:1]
	v_add_co_u32_e32 v12, vcc, s4, v26
	s_waitcnt lgkmcnt(0)
	s_nop 1
	v_add_f32_dpp v28, v28, v28 quad_perm:[2,3,0,1] row_mask:0xf bank_mask:0xf
	v_addc_co_u32_e32 v13, vcc, 0, v27, vcc
	global_store_dwordx2 v[12:13], v[10:11], off offset:1024
	v_cvt_pk_bf16_f32 v10, v14, v15
	s_waitcnt lgkmcnt(0)
	s_nop 1
	v_add_f32_dpp v26, v28, v28 row_half_mirror row_mask:0xf bank_mask:0xf
	v_cvt_pk_bf16_f32 v11, v16, v17
	global_store_dwordx2 v[12:13], v[10:11], off offset:1536
	v_cvt_pk_bf16_f32 v14, v18, v19
	v_cvt_pk_bf16_f32 v15, v20, v21
	s_waitcnt lgkmcnt(0)
	s_nop 1
	v_add_f32_dpp v26, v26, v26 row_mirror row_mask:0xf bank_mask:0xf
	global_store_dwordx2 v[12:13], v[14:15], off offset:2048
	v_cvt_pk_bf16_f32 v14, v22, v23
	v_cvt_pk_bf16_f32 v15, v24, v25
	global_store_dwordx2 v[12:13], v[14:15], off offset:2560
	s_waitcnt lgkmcnt(0)
	v_mov_b32_e32 v27, v26
	v_mov_b32_e32 v10, v26
	s_nop 1
	v_permlane16_swap_b32_e32 v27, v10
	s_nop 1
	v_add_f32_e32 v10, v27, v10
	v_mov_b32_e32 v11, v10
	s_nop 1
	v_permlane32_swap_b32_e32 v11, v10
	s_nop 1
	s_and_saveexec_b64 s[4:5], s[38:39]
	s_cbranch_execz .LBB0_1379
	s_waitcnt lgkmcnt(0)
	v_add_f32_e32 v10, v10, v11
	v_fmamk_f32 v10, v10, 0x3a800000, v219
	v_mul_f32_e32 v11, 0x4b800000, v10
	v_cmp_gt_f32_e32 vcc, s35, v10
	s_add_u32 s8, s70, s2
	s_addc_u32 s9, s71, s3
	v_cndmask_b32_e32 v10, v10, v11, vcc
	v_rsq_f32_e32 v10, v10
	s_nop 0
	v_mul_f32_e32 v11, 0x45800000, v10
	v_cndmask_b32_e32 v10, v10, v11, vcc
	global_store_dword v3, v10, s[8:9]
	s_branch .LBB0_1379
